# P3 and P5 tile loops hand-written too: scalar-base LDS-DMA staging, continuous-DMA K loop, next tile staged under the pipelined residual epilogue
# speedup vs baseline: 1.0900x; 1.0356x over previous
.LBB0_1000:
	s_lshr_b32 s2, s29, 5
	s_lshl_b32 s2, s2, 3
	s_and_b32 s3, s29, 7
	s_add_i32 s20, s2, s3
	s_bfe_u32 s19, s29, 0x20003
	s_lshl_b32 s2, s20, 19
	s_add_u32 s36, s64, s2
	s_addc_u32 s37, s65, 0
	s_lshl_b32 s2, s19, 19
	s_add_u32 s38, s7, s2
	s_addc_u32 s39, s28, 0
	v_lshrrev_b32_e32 v194, 3, v222
	v_lshrrev_b32_e32 v195, 4, v222
	v_xor_b32_e32 v195, v195, v222
	v_and_b32_e32 v195, 7, v195
	v_lshlrev_b32_e32 v195, 4, v195
	v_lshlrev_b32_e32 v194, 11, v194
	v_add_u32_e32 v1, v194, v195
	v_readfirstlane_b32 s21, v222
	s_nop 3
	s_lshr_b32 s22, s21, 8
	s_lshr_b32 s21, s21, 6
	s_lshl_b32 s21, s21, 10
	s_barrier
	s_mov_b32 m0, s21
	s_nop 0
	global_load_lds_dwordx4 v1, s[36:37]
	s_add_i32 m0, s21, 0x2000
	s_add_u32 s40, s36, 0x20000
	s_addc_u32 s41, s37, 0
	global_load_lds_dwordx4 v1, s[40:41]
	s_add_i32 m0, s21, 0x4000
	s_add_u32 s40, s36, 0x40000
	s_addc_u32 s41, s37, 0
	global_load_lds_dwordx4 v1, s[40:41]
	s_add_i32 m0, s21, 0x6000
	s_add_u32 s40, s36, 0x60000
	s_addc_u32 s41, s37, 0
	global_load_lds_dwordx4 v1, s[40:41]
	s_add_i32 m0, s21, 0x8000
	s_nop 0
	global_load_lds_dwordx4 v1, s[38:39]
	s_add_i32 m0, s21, 0xa000
	s_add_u32 s40, s38, 0x20000
	s_addc_u32 s41, s39, 0
	global_load_lds_dwordx4 v1, s[40:41]
	s_add_i32 m0, s21, 0xc000
	s_add_u32 s40, s38, 0x40000
	s_addc_u32 s41, s39, 0
	global_load_lds_dwordx4 v1, s[40:41]
	s_add_i32 m0, s21, 0xe000
	s_add_u32 s40, s38, 0x60000
	s_addc_u32 s41, s39, 0
	global_load_lds_dwordx4 v1, s[40:41]
	s_waitcnt vmcnt(0)
.Lp3_cont:
	v_and_b32_e32 v194, 15, v222
	v_bfe_u32 v195, v222, 4, 2
	v_bfe_u32 v196, v194, 1, 3
	v_xor_b32_e32 v195, v195, v196
	v_lshlrev_b32_e32 v195, 4, v195
	v_lshrrev_b32_e32 v196, 8, v222
	v_lshl_or_b32 v196, v196, 7, v194
	v_lshl_or_b32 v200, v196, 7, v195
	v_xor_b32_e32 v201, 64, v200
	v_bfe_u32 v196, v222, 6, 2
	v_lshl_or_b32 v196, v196, 6, v194
	v_lshl_or_b32 v202, v196, 7, v195
	v_xor_b32_e32 v203, 64, v202
	v_add_u32_e32 v204, 0x10000, v200
	v_add_u32_e32 v205, 0x10000, v201
	v_add_u32_e32 v206, 0x10000, v202
	v_add_u32_e32 v207, 0x10000, v203
	v_readfirstlane_b32 s21, v222
	s_nop 3
	s_lshr_b32 s22, s21, 8
	s_lshr_b32 s21, s21, 6
	s_lshl_b32 s21, s21, 10
	s_barrier
	s_add_i32 m0, s21, 0x10000
	s_add_u32 s40, s36, 0x80
	s_addc_u32 s41, s37, 0
	global_load_lds_dwordx4 v1, s[40:41]
	s_add_i32 m0, s21, 0x18000
	s_add_u32 s40, s38, 0x80
	s_addc_u32 s41, s39, 0
	global_load_lds_dwordx4 v1, s[40:41]
	s_waitcnt vmcnt(54)
	s_barrier
	s_cmp_eq_u32 s22, 0
	s_cbranch_scc1 .Lp3_skew0
	s_barrier
.Lp3_skew0:
	ds_read_b128 v[130:133], v200 offset:0
	ds_read_b128 v[134:137], v200 offset:2048
	ds_read_b128 v[138:141], v200 offset:4096
	ds_read_b128 v[142:145], v200 offset:6144
	ds_read_b128 v[162:165], v202 offset:32768
	ds_read_b128 v[166:169], v202 offset:34816
	ds_read_b128 v[170:173], v202 offset:36864
	ds_read_b128 v[174:177], v202 offset:38912
	s_add_i32 m0, s21, 0x14000
	s_add_u32 s40, s36, 0x40080
	s_addc_u32 s41, s37, 0
	global_load_lds_dwordx4 v1, s[40:41]
	s_add_i32 m0, s21, 0x1a000
	s_add_u32 s40, s38, 0x20080
	s_addc_u32 s41, s39, 0
	global_load_lds_dwordx4 v1, s[40:41]
	s_waitcnt lgkmcnt(0)
	s_barrier
	v_mfma_f32_16x16x32_f16 v[126:129], v[162:165], v[130:133], 0
	v_mfma_f32_16x16x32_f16 v[122:125], v[166:169], v[130:133], 0
	v_mfma_f32_16x16x32_f16 v[118:121], v[170:173], v[130:133], 0
	v_mfma_f32_16x16x32_f16 v[114:117], v[174:177], v[130:133], 0
	v_mfma_f32_16x16x32_f16 v[110:113], v[162:165], v[134:137], 0
	v_mfma_f32_16x16x32_f16 v[106:109], v[166:169], v[134:137], 0
	v_mfma_f32_16x16x32_f16 v[102:105], v[170:173], v[134:137], 0
	v_mfma_f32_16x16x32_f16 v[98:101], v[174:177], v[134:137], 0
	v_mfma_f32_16x16x32_f16 v[94:97], v[162:165], v[138:141], 0
	v_mfma_f32_16x16x32_f16 v[90:93], v[166:169], v[138:141], 0
	v_mfma_f32_16x16x32_f16 v[86:89], v[170:173], v[138:141], 0
	v_mfma_f32_16x16x32_f16 v[82:85], v[174:177], v[138:141], 0
	v_mfma_f32_16x16x32_f16 v[78:81], v[162:165], v[142:145], 0
	v_mfma_f32_16x16x32_f16 v[74:77], v[166:169], v[142:145], 0
	v_mfma_f32_16x16x32_f16 v[70:73], v[170:173], v[142:145], 0
	v_mfma_f32_16x16x32_f16 v[66:69], v[174:177], v[142:145], 0
	s_barrier
	ds_read_b128 v[146:149], v200 offset:8192
	ds_read_b128 v[150:153], v200 offset:10240
	ds_read_b128 v[154:157], v200 offset:12288
	ds_read_b128 v[158:161], v200 offset:14336
	s_add_i32 m0, s21, 0x1c000
	s_add_u32 s40, s38, 0x40080
	s_addc_u32 s41, s39, 0
	global_load_lds_dwordx4 v1, s[40:41]
	s_add_i32 m0, s21, 0x1e000
	s_add_u32 s40, s38, 0x60080
	s_addc_u32 s41, s39, 0
	global_load_lds_dwordx4 v1, s[40:41]
	s_waitcnt lgkmcnt(0)
	s_barrier
	v_mfma_f32_16x16x32_f16 v[62:65], v[162:165], v[146:149], 0
	v_mfma_f32_16x16x32_f16 v[58:61], v[166:169], v[146:149], 0
	v_mfma_f32_16x16x32_f16 v[54:57], v[170:173], v[146:149], 0
	v_mfma_f32_16x16x32_f16 v[50:53], v[174:177], v[146:149], 0
	v_mfma_f32_16x16x32_f16 v[46:49], v[162:165], v[150:153], 0
	v_mfma_f32_16x16x32_f16 v[42:45], v[166:169], v[150:153], 0
	v_mfma_f32_16x16x32_f16 v[38:41], v[170:173], v[150:153], 0
	v_mfma_f32_16x16x32_f16 v[34:37], v[174:177], v[150:153], 0
	v_mfma_f32_16x16x32_f16 v[30:33], v[162:165], v[154:157], 0
	v_mfma_f32_16x16x32_f16 v[26:29], v[166:169], v[154:157], 0
	v_mfma_f32_16x16x32_f16 v[22:25], v[170:173], v[154:157], 0
	v_mfma_f32_16x16x32_f16 v[18:21], v[174:177], v[154:157], 0
	v_mfma_f32_16x16x32_f16 v[14:17], v[162:165], v[158:161], 0
	v_mfma_f32_16x16x32_f16 v[10:13], v[166:169], v[158:161], 0
	v_mfma_f32_16x16x32_f16 v[6:9], v[170:173], v[158:161], 0
	v_mfma_f32_16x16x32_f16 v[2:5], v[174:177], v[158:161], 0
	s_barrier
	ds_read_b128 v[130:133], v201 offset:0
	ds_read_b128 v[134:137], v201 offset:2048
	ds_read_b128 v[138:141], v201 offset:4096
	ds_read_b128 v[142:145], v201 offset:6144
	ds_read_b128 v[162:165], v203 offset:32768
	ds_read_b128 v[166:169], v203 offset:34816
	ds_read_b128 v[170:173], v203 offset:36864
	ds_read_b128 v[174:177], v203 offset:38912
	s_add_i32 m0, s21, 0x12000
	s_add_u32 s40, s36, 0x20080
	s_addc_u32 s41, s37, 0
	global_load_lds_dwordx4 v1, s[40:41]
	s_add_i32 m0, s21, 0x16000
	s_add_u32 s40, s36, 0x60080
	s_addc_u32 s41, s37, 0
	global_load_lds_dwordx4 v1, s[40:41]
	s_waitcnt lgkmcnt(0)
	s_barrier
	v_mfma_f32_16x16x32_f16 v[126:129], v[162:165], v[130:133], v[126:129]
	v_mfma_f32_16x16x32_f16 v[122:125], v[166:169], v[130:133], v[122:125]
	v_mfma_f32_16x16x32_f16 v[118:121], v[170:173], v[130:133], v[118:121]
	v_mfma_f32_16x16x32_f16 v[114:117], v[174:177], v[130:133], v[114:117]
	v_mfma_f32_16x16x32_f16 v[110:113], v[162:165], v[134:137], v[110:113]
	v_mfma_f32_16x16x32_f16 v[106:109], v[166:169], v[134:137], v[106:109]
	v_mfma_f32_16x16x32_f16 v[102:105], v[170:173], v[134:137], v[102:105]
	v_mfma_f32_16x16x32_f16 v[98:101], v[174:177], v[134:137], v[98:101]
	v_mfma_f32_16x16x32_f16 v[94:97], v[162:165], v[138:141], v[94:97]
	v_mfma_f32_16x16x32_f16 v[90:93], v[166:169], v[138:141], v[90:93]
	v_mfma_f32_16x16x32_f16 v[86:89], v[170:173], v[138:141], v[86:89]
	v_mfma_f32_16x16x32_f16 v[82:85], v[174:177], v[138:141], v[82:85]
	v_mfma_f32_16x16x32_f16 v[78:81], v[162:165], v[142:145], v[78:81]
	v_mfma_f32_16x16x32_f16 v[74:77], v[166:169], v[142:145], v[74:77]
	v_mfma_f32_16x16x32_f16 v[70:73], v[170:173], v[142:145], v[70:73]
	v_mfma_f32_16x16x32_f16 v[66:69], v[174:177], v[142:145], v[66:69]
	s_barrier
	ds_read_b128 v[146:149], v201 offset:8192
	ds_read_b128 v[150:153], v201 offset:10240
	ds_read_b128 v[154:157], v201 offset:12288
	ds_read_b128 v[158:161], v201 offset:14336
	s_mov_b32 m0, s21
	s_add_u32 s40, s36, 0x100
	s_addc_u32 s41, s37, 0
	global_load_lds_dwordx4 v1, s[40:41]
	s_add_i32 m0, s21, 0x8000
	s_add_u32 s40, s38, 0x100
	s_addc_u32 s41, s39, 0
	global_load_lds_dwordx4 v1, s[40:41]
	s_waitcnt vmcnt(4) lgkmcnt(0)
	s_barrier
	v_mfma_f32_16x16x32_f16 v[62:65], v[162:165], v[146:149], v[62:65]
	v_mfma_f32_16x16x32_f16 v[58:61], v[166:169], v[146:149], v[58:61]
	v_mfma_f32_16x16x32_f16 v[54:57], v[170:173], v[146:149], v[54:57]
	v_mfma_f32_16x16x32_f16 v[50:53], v[174:177], v[146:149], v[50:53]
	v_mfma_f32_16x16x32_f16 v[46:49], v[162:165], v[150:153], v[46:49]
	v_mfma_f32_16x16x32_f16 v[42:45], v[166:169], v[150:153], v[42:45]
	v_mfma_f32_16x16x32_f16 v[38:41], v[170:173], v[150:153], v[38:41]
	v_mfma_f32_16x16x32_f16 v[34:37], v[174:177], v[150:153], v[34:37]
	v_mfma_f32_16x16x32_f16 v[30:33], v[162:165], v[154:157], v[30:33]
	v_mfma_f32_16x16x32_f16 v[26:29], v[166:169], v[154:157], v[26:29]
	v_mfma_f32_16x16x32_f16 v[22:25], v[170:173], v[154:157], v[22:25]
	v_mfma_f32_16x16x32_f16 v[18:21], v[174:177], v[154:157], v[18:21]
	v_mfma_f32_16x16x32_f16 v[14:17], v[162:165], v[158:161], v[14:17]
	v_mfma_f32_16x16x32_f16 v[10:13], v[166:169], v[158:161], v[10:13]
	v_mfma_f32_16x16x32_f16 v[6:9], v[170:173], v[158:161], v[6:9]
	v_mfma_f32_16x16x32_f16 v[2:5], v[174:177], v[158:161], v[2:5]
	s_barrier
	s_add_u32 s36, s36, 0x80
	s_addc_u32 s37, s37, 0
	s_add_u32 s38, s38, 0x80
	s_addc_u32 s39, s39, 0
	ds_read_b128 v[130:133], v204 offset:0
	ds_read_b128 v[134:137], v204 offset:2048
	ds_read_b128 v[138:141], v204 offset:4096
	ds_read_b128 v[142:145], v204 offset:6144
	ds_read_b128 v[162:165], v206 offset:32768
	ds_read_b128 v[166:169], v206 offset:34816
	ds_read_b128 v[170:173], v206 offset:36864
	ds_read_b128 v[174:177], v206 offset:38912
	s_add_i32 m0, s21, 0x4000
	s_add_u32 s40, s36, 0x40080
	s_addc_u32 s41, s37, 0
	global_load_lds_dwordx4 v1, s[40:41]
	s_add_i32 m0, s21, 0xa000
	s_add_u32 s40, s38, 0x20080
	s_addc_u32 s41, s39, 0
	global_load_lds_dwordx4 v1, s[40:41]
	s_waitcnt vmcnt(4) lgkmcnt(0)
	s_barrier
	v_mfma_f32_16x16x32_f16 v[126:129], v[162:165], v[130:133], v[126:129]
	v_mfma_f32_16x16x32_f16 v[122:125], v[166:169], v[130:133], v[122:125]
	v_mfma_f32_16x16x32_f16 v[118:121], v[170:173], v[130:133], v[118:121]
	v_mfma_f32_16x16x32_f16 v[114:117], v[174:177], v[130:133], v[114:117]
	v_mfma_f32_16x16x32_f16 v[110:113], v[162:165], v[134:137], v[110:113]
	v_mfma_f32_16x16x32_f16 v[106:109], v[166:169], v[134:137], v[106:109]
	v_mfma_f32_16x16x32_f16 v[102:105], v[170:173], v[134:137], v[102:105]
	v_mfma_f32_16x16x32_f16 v[98:101], v[174:177], v[134:137], v[98:101]
	v_mfma_f32_16x16x32_f16 v[94:97], v[162:165], v[138:141], v[94:97]
	v_mfma_f32_16x16x32_f16 v[90:93], v[166:169], v[138:141], v[90:93]
	v_mfma_f32_16x16x32_f16 v[86:89], v[170:173], v[138:141], v[86:89]
	v_mfma_f32_16x16x32_f16 v[82:85], v[174:177], v[138:141], v[82:85]
	v_mfma_f32_16x16x32_f16 v[78:81], v[162:165], v[142:145], v[78:81]
	v_mfma_f32_16x16x32_f16 v[74:77], v[166:169], v[142:145], v[74:77]
	v_mfma_f32_16x16x32_f16 v[70:73], v[170:173], v[142:145], v[70:73]
	v_mfma_f32_16x16x32_f16 v[66:69], v[174:177], v[142:145], v[66:69]
	s_barrier
	ds_read_b128 v[146:149], v204 offset:8192
	ds_read_b128 v[150:153], v204 offset:10240
	ds_read_b128 v[154:157], v204 offset:12288
	ds_read_b128 v[158:161], v204 offset:14336
	s_add_i32 m0, s21, 0xc000
	s_add_u32 s40, s38, 0x40080
	s_addc_u32 s41, s39, 0
	global_load_lds_dwordx4 v1, s[40:41]
	s_add_i32 m0, s21, 0xe000
	s_add_u32 s40, s38, 0x60080
	s_addc_u32 s41, s39, 0
	global_load_lds_dwordx4 v1, s[40:41]
	s_waitcnt lgkmcnt(0)
	s_barrier
	v_mfma_f32_16x16x32_f16 v[62:65], v[162:165], v[146:149], v[62:65]
	v_mfma_f32_16x16x32_f16 v[58:61], v[166:169], v[146:149], v[58:61]
	v_mfma_f32_16x16x32_f16 v[54:57], v[170:173], v[146:149], v[54:57]
	v_mfma_f32_16x16x32_f16 v[50:53], v[174:177], v[146:149], v[50:53]
	v_mfma_f32_16x16x32_f16 v[46:49], v[162:165], v[150:153], v[46:49]
	v_mfma_f32_16x16x32_f16 v[42:45], v[166:169], v[150:153], v[42:45]
	v_mfma_f32_16x16x32_f16 v[38:41], v[170:173], v[150:153], v[38:41]
	v_mfma_f32_16x16x32_f16 v[34:37], v[174:177], v[150:153], v[34:37]
	v_mfma_f32_16x16x32_f16 v[30:33], v[162:165], v[154:157], v[30:33]
	v_mfma_f32_16x16x32_f16 v[26:29], v[166:169], v[154:157], v[26:29]
	v_mfma_f32_16x16x32_f16 v[22:25], v[170:173], v[154:157], v[22:25]
	v_mfma_f32_16x16x32_f16 v[18:21], v[174:177], v[154:157], v[18:21]
	v_mfma_f32_16x16x32_f16 v[14:17], v[162:165], v[158:161], v[14:17]
	v_mfma_f32_16x16x32_f16 v[10:13], v[166:169], v[158:161], v[10:13]
	v_mfma_f32_16x16x32_f16 v[6:9], v[170:173], v[158:161], v[6:9]
	v_mfma_f32_16x16x32_f16 v[2:5], v[174:177], v[158:161], v[2:5]
	s_barrier
	ds_read_b128 v[130:133], v205 offset:0
	ds_read_b128 v[134:137], v205 offset:2048
	ds_read_b128 v[138:141], v205 offset:4096
	ds_read_b128 v[142:145], v205 offset:6144
	ds_read_b128 v[162:165], v207 offset:32768
	ds_read_b128 v[166:169], v207 offset:34816
	ds_read_b128 v[170:173], v207 offset:36864
	ds_read_b128 v[174:177], v207 offset:38912
	s_add_i32 m0, s21, 0x2000
	s_add_u32 s40, s36, 0x20080
	s_addc_u32 s41, s37, 0
	global_load_lds_dwordx4 v1, s[40:41]
	s_add_i32 m0, s21, 0x6000
	s_add_u32 s40, s36, 0x60080
	s_addc_u32 s41, s37, 0
	global_load_lds_dwordx4 v1, s[40:41]
	s_waitcnt lgkmcnt(0)
	s_barrier
	v_mfma_f32_16x16x32_f16 v[126:129], v[162:165], v[130:133], v[126:129]
	v_mfma_f32_16x16x32_f16 v[122:125], v[166:169], v[130:133], v[122:125]
	v_mfma_f32_16x16x32_f16 v[118:121], v[170:173], v[130:133], v[118:121]
	v_mfma_f32_16x16x32_f16 v[114:117], v[174:177], v[130:133], v[114:117]
	v_mfma_f32_16x16x32_f16 v[110:113], v[162:165], v[134:137], v[110:113]
	v_mfma_f32_16x16x32_f16 v[106:109], v[166:169], v[134:137], v[106:109]
	v_mfma_f32_16x16x32_f16 v[102:105], v[170:173], v[134:137], v[102:105]
	v_mfma_f32_16x16x32_f16 v[98:101], v[174:177], v[134:137], v[98:101]
	v_mfma_f32_16x16x32_f16 v[94:97], v[162:165], v[138:141], v[94:97]
	v_mfma_f32_16x16x32_f16 v[90:93], v[166:169], v[138:141], v[90:93]
	v_mfma_f32_16x16x32_f16 v[86:89], v[170:173], v[138:141], v[86:89]
	v_mfma_f32_16x16x32_f16 v[82:85], v[174:177], v[138:141], v[82:85]
	v_mfma_f32_16x16x32_f16 v[78:81], v[162:165], v[142:145], v[78:81]
	v_mfma_f32_16x16x32_f16 v[74:77], v[166:169], v[142:145], v[74:77]
	v_mfma_f32_16x16x32_f16 v[70:73], v[170:173], v[142:145], v[70:73]
	v_mfma_f32_16x16x32_f16 v[66:69], v[174:177], v[142:145], v[66:69]
	s_barrier
	ds_read_b128 v[146:149], v205 offset:8192
	ds_read_b128 v[150:153], v205 offset:10240
	ds_read_b128 v[154:157], v205 offset:12288
	ds_read_b128 v[158:161], v205 offset:14336
	s_add_i32 m0, s21, 0x10000
	s_add_u32 s40, s36, 0x100
	s_addc_u32 s41, s37, 0
	global_load_lds_dwordx4 v1, s[40:41]
	s_add_i32 m0, s21, 0x18000
	s_add_u32 s40, s38, 0x100
	s_addc_u32 s41, s39, 0
	global_load_lds_dwordx4 v1, s[40:41]
	s_waitcnt vmcnt(4) lgkmcnt(0)
	s_barrier
	v_mfma_f32_16x16x32_f16 v[62:65], v[162:165], v[146:149], v[62:65]
	v_mfma_f32_16x16x32_f16 v[58:61], v[166:169], v[146:149], v[58:61]
	v_mfma_f32_16x16x32_f16 v[54:57], v[170:173], v[146:149], v[54:57]
	v_mfma_f32_16x16x32_f16 v[50:53], v[174:177], v[146:149], v[50:53]
	v_mfma_f32_16x16x32_f16 v[46:49], v[162:165], v[150:153], v[46:49]
	v_mfma_f32_16x16x32_f16 v[42:45], v[166:169], v[150:153], v[42:45]
	v_mfma_f32_16x16x32_f16 v[38:41], v[170:173], v[150:153], v[38:41]
	v_mfma_f32_16x16x32_f16 v[34:37], v[174:177], v[150:153], v[34:37]
	v_mfma_f32_16x16x32_f16 v[30:33], v[162:165], v[154:157], v[30:33]
	v_mfma_f32_16x16x32_f16 v[26:29], v[166:169], v[154:157], v[26:29]
	v_mfma_f32_16x16x32_f16 v[22:25], v[170:173], v[154:157], v[22:25]
	v_mfma_f32_16x16x32_f16 v[18:21], v[174:177], v[154:157], v[18:21]
	v_mfma_f32_16x16x32_f16 v[14:17], v[162:165], v[158:161], v[14:17]
	v_mfma_f32_16x16x32_f16 v[10:13], v[166:169], v[158:161], v[10:13]
	v_mfma_f32_16x16x32_f16 v[6:9], v[170:173], v[158:161], v[6:9]
	v_mfma_f32_16x16x32_f16 v[2:5], v[174:177], v[158:161], v[2:5]
	s_barrier
	s_add_u32 s36, s36, 0x80
	s_addc_u32 s37, s37, 0
	s_add_u32 s38, s38, 0x80
	s_addc_u32 s39, s39, 0
	s_movk_i32 s23, 6
.Lp3_loop:
	ds_read_b128 v[130:133], v200 offset:0
	ds_read_b128 v[134:137], v200 offset:2048
	ds_read_b128 v[138:141], v200 offset:4096
	ds_read_b128 v[142:145], v200 offset:6144
	ds_read_b128 v[162:165], v202 offset:32768
	ds_read_b128 v[166:169], v202 offset:34816
	ds_read_b128 v[170:173], v202 offset:36864
	ds_read_b128 v[174:177], v202 offset:38912
	s_add_i32 m0, s21, 0x14000
	s_add_u32 s40, s36, 0x40080
	s_addc_u32 s41, s37, 0
	global_load_lds_dwordx4 v1, s[40:41]
	s_add_i32 m0, s21, 0x1a000
	s_add_u32 s40, s38, 0x20080
	s_addc_u32 s41, s39, 0
	global_load_lds_dwordx4 v1, s[40:41]
	s_waitcnt vmcnt(4) lgkmcnt(0)
	s_barrier
	v_mfma_f32_16x16x32_f16 v[126:129], v[162:165], v[130:133], v[126:129]
	v_mfma_f32_16x16x32_f16 v[122:125], v[166:169], v[130:133], v[122:125]
	v_mfma_f32_16x16x32_f16 v[118:121], v[170:173], v[130:133], v[118:121]
	v_mfma_f32_16x16x32_f16 v[114:117], v[174:177], v[130:133], v[114:117]
	v_mfma_f32_16x16x32_f16 v[110:113], v[162:165], v[134:137], v[110:113]
	v_mfma_f32_16x16x32_f16 v[106:109], v[166:169], v[134:137], v[106:109]
	v_mfma_f32_16x16x32_f16 v[102:105], v[170:173], v[134:137], v[102:105]
	v_mfma_f32_16x16x32_f16 v[98:101], v[174:177], v[134:137], v[98:101]
	v_mfma_f32_16x16x32_f16 v[94:97], v[162:165], v[138:141], v[94:97]
	v_mfma_f32_16x16x32_f16 v[90:93], v[166:169], v[138:141], v[90:93]
	v_mfma_f32_16x16x32_f16 v[86:89], v[170:173], v[138:141], v[86:89]
	v_mfma_f32_16x16x32_f16 v[82:85], v[174:177], v[138:141], v[82:85]
	v_mfma_f32_16x16x32_f16 v[78:81], v[162:165], v[142:145], v[78:81]
	v_mfma_f32_16x16x32_f16 v[74:77], v[166:169], v[142:145], v[74:77]
	v_mfma_f32_16x16x32_f16 v[70:73], v[170:173], v[142:145], v[70:73]
	v_mfma_f32_16x16x32_f16 v[66:69], v[174:177], v[142:145], v[66:69]
	s_barrier
	ds_read_b128 v[146:149], v200 offset:8192
	ds_read_b128 v[150:153], v200 offset:10240
	ds_read_b128 v[154:157], v200 offset:12288
	ds_read_b128 v[158:161], v200 offset:14336
	s_add_i32 m0, s21, 0x1c000
	s_add_u32 s40, s38, 0x40080
	s_addc_u32 s41, s39, 0
	global_load_lds_dwordx4 v1, s[40:41]
	s_add_i32 m0, s21, 0x1e000
	s_add_u32 s40, s38, 0x60080
	s_addc_u32 s41, s39, 0
	global_load_lds_dwordx4 v1, s[40:41]
	s_waitcnt lgkmcnt(0)
	s_barrier
	v_mfma_f32_16x16x32_f16 v[62:65], v[162:165], v[146:149], v[62:65]
	v_mfma_f32_16x16x32_f16 v[58:61], v[166:169], v[146:149], v[58:61]
	v_mfma_f32_16x16x32_f16 v[54:57], v[170:173], v[146:149], v[54:57]
	v_mfma_f32_16x16x32_f16 v[50:53], v[174:177], v[146:149], v[50:53]
	v_mfma_f32_16x16x32_f16 v[46:49], v[162:165], v[150:153], v[46:49]
	v_mfma_f32_16x16x32_f16 v[42:45], v[166:169], v[150:153], v[42:45]
	v_mfma_f32_16x16x32_f16 v[38:41], v[170:173], v[150:153], v[38:41]
	v_mfma_f32_16x16x32_f16 v[34:37], v[174:177], v[150:153], v[34:37]
	v_mfma_f32_16x16x32_f16 v[30:33], v[162:165], v[154:157], v[30:33]
	v_mfma_f32_16x16x32_f16 v[26:29], v[166:169], v[154:157], v[26:29]
	v_mfma_f32_16x16x32_f16 v[22:25], v[170:173], v[154:157], v[22:25]
	v_mfma_f32_16x16x32_f16 v[18:21], v[174:177], v[154:157], v[18:21]
	v_mfma_f32_16x16x32_f16 v[14:17], v[162:165], v[158:161], v[14:17]
	v_mfma_f32_16x16x32_f16 v[10:13], v[166:169], v[158:161], v[10:13]
	v_mfma_f32_16x16x32_f16 v[6:9], v[170:173], v[158:161], v[6:9]
	v_mfma_f32_16x16x32_f16 v[2:5], v[174:177], v[158:161], v[2:5]
	s_barrier
	ds_read_b128 v[130:133], v201 offset:0
	ds_read_b128 v[134:137], v201 offset:2048
	ds_read_b128 v[138:141], v201 offset:4096
	ds_read_b128 v[142:145], v201 offset:6144
	ds_read_b128 v[162:165], v203 offset:32768
	ds_read_b128 v[166:169], v203 offset:34816
	ds_read_b128 v[170:173], v203 offset:36864
	ds_read_b128 v[174:177], v203 offset:38912
	s_add_i32 m0, s21, 0x12000
	s_add_u32 s40, s36, 0x20080
	s_addc_u32 s41, s37, 0
	global_load_lds_dwordx4 v1, s[40:41]
	s_add_i32 m0, s21, 0x16000
	s_add_u32 s40, s36, 0x60080
	s_addc_u32 s41, s37, 0
	global_load_lds_dwordx4 v1, s[40:41]
	s_waitcnt lgkmcnt(0)
	s_barrier
	v_mfma_f32_16x16x32_f16 v[126:129], v[162:165], v[130:133], v[126:129]
	v_mfma_f32_16x16x32_f16 v[122:125], v[166:169], v[130:133], v[122:125]
	v_mfma_f32_16x16x32_f16 v[118:121], v[170:173], v[130:133], v[118:121]
	v_mfma_f32_16x16x32_f16 v[114:117], v[174:177], v[130:133], v[114:117]
	v_mfma_f32_16x16x32_f16 v[110:113], v[162:165], v[134:137], v[110:113]
	v_mfma_f32_16x16x32_f16 v[106:109], v[166:169], v[134:137], v[106:109]
	v_mfma_f32_16x16x32_f16 v[102:105], v[170:173], v[134:137], v[102:105]
	v_mfma_f32_16x16x32_f16 v[98:101], v[174:177], v[134:137], v[98:101]
	v_mfma_f32_16x16x32_f16 v[94:97], v[162:165], v[138:141], v[94:97]
	v_mfma_f32_16x16x32_f16 v[90:93], v[166:169], v[138:141], v[90:93]
	v_mfma_f32_16x16x32_f16 v[86:89], v[170:173], v[138:141], v[86:89]
	v_mfma_f32_16x16x32_f16 v[82:85], v[174:177], v[138:141], v[82:85]
	v_mfma_f32_16x16x32_f16 v[78:81], v[162:165], v[142:145], v[78:81]
	v_mfma_f32_16x16x32_f16 v[74:77], v[166:169], v[142:145], v[74:77]
	v_mfma_f32_16x16x32_f16 v[70:73], v[170:173], v[142:145], v[70:73]
	v_mfma_f32_16x16x32_f16 v[66:69], v[174:177], v[142:145], v[66:69]
	s_barrier
	ds_read_b128 v[146:149], v201 offset:8192
	ds_read_b128 v[150:153], v201 offset:10240
	ds_read_b128 v[154:157], v201 offset:12288
	ds_read_b128 v[158:161], v201 offset:14336
	s_mov_b32 m0, s21
	s_add_u32 s40, s36, 0x100
	s_addc_u32 s41, s37, 0
	global_load_lds_dwordx4 v1, s[40:41]
	s_add_i32 m0, s21, 0x8000
	s_add_u32 s40, s38, 0x100
	s_addc_u32 s41, s39, 0
	global_load_lds_dwordx4 v1, s[40:41]
	s_waitcnt vmcnt(4) lgkmcnt(0)
	s_barrier
	v_mfma_f32_16x16x32_f16 v[62:65], v[162:165], v[146:149], v[62:65]
	v_mfma_f32_16x16x32_f16 v[58:61], v[166:169], v[146:149], v[58:61]
	v_mfma_f32_16x16x32_f16 v[54:57], v[170:173], v[146:149], v[54:57]
	v_mfma_f32_16x16x32_f16 v[50:53], v[174:177], v[146:149], v[50:53]
	v_mfma_f32_16x16x32_f16 v[46:49], v[162:165], v[150:153], v[46:49]
	v_mfma_f32_16x16x32_f16 v[42:45], v[166:169], v[150:153], v[42:45]
	v_mfma_f32_16x16x32_f16 v[38:41], v[170:173], v[150:153], v[38:41]
	v_mfma_f32_16x16x32_f16 v[34:37], v[174:177], v[150:153], v[34:37]
	v_mfma_f32_16x16x32_f16 v[30:33], v[162:165], v[154:157], v[30:33]
	v_mfma_f32_16x16x32_f16 v[26:29], v[166:169], v[154:157], v[26:29]
	v_mfma_f32_16x16x32_f16 v[22:25], v[170:173], v[154:157], v[22:25]
	v_mfma_f32_16x16x32_f16 v[18:21], v[174:177], v[154:157], v[18:21]
	v_mfma_f32_16x16x32_f16 v[14:17], v[162:165], v[158:161], v[14:17]
	v_mfma_f32_16x16x32_f16 v[10:13], v[166:169], v[158:161], v[10:13]
	v_mfma_f32_16x16x32_f16 v[6:9], v[170:173], v[158:161], v[6:9]
	v_mfma_f32_16x16x32_f16 v[2:5], v[174:177], v[158:161], v[2:5]
	s_barrier
	s_add_u32 s36, s36, 0x80
	s_addc_u32 s37, s37, 0
	s_add_u32 s38, s38, 0x80
	s_addc_u32 s39, s39, 0
	ds_read_b128 v[130:133], v204 offset:0
	ds_read_b128 v[134:137], v204 offset:2048
	ds_read_b128 v[138:141], v204 offset:4096
	ds_read_b128 v[142:145], v204 offset:6144
	ds_read_b128 v[162:165], v206 offset:32768
	ds_read_b128 v[166:169], v206 offset:34816
	ds_read_b128 v[170:173], v206 offset:36864
	ds_read_b128 v[174:177], v206 offset:38912
	s_add_i32 m0, s21, 0x4000
	s_add_u32 s40, s36, 0x40080
	s_addc_u32 s41, s37, 0
	global_load_lds_dwordx4 v1, s[40:41]
	s_add_i32 m0, s21, 0xa000
	s_add_u32 s40, s38, 0x20080
	s_addc_u32 s41, s39, 0
	global_load_lds_dwordx4 v1, s[40:41]
	s_waitcnt vmcnt(4) lgkmcnt(0)
	s_barrier
	v_mfma_f32_16x16x32_f16 v[126:129], v[162:165], v[130:133], v[126:129]
	v_mfma_f32_16x16x32_f16 v[122:125], v[166:169], v[130:133], v[122:125]
	v_mfma_f32_16x16x32_f16 v[118:121], v[170:173], v[130:133], v[118:121]
	v_mfma_f32_16x16x32_f16 v[114:117], v[174:177], v[130:133], v[114:117]
	v_mfma_f32_16x16x32_f16 v[110:113], v[162:165], v[134:137], v[110:113]
	v_mfma_f32_16x16x32_f16 v[106:109], v[166:169], v[134:137], v[106:109]
	v_mfma_f32_16x16x32_f16 v[102:105], v[170:173], v[134:137], v[102:105]
	v_mfma_f32_16x16x32_f16 v[98:101], v[174:177], v[134:137], v[98:101]
	v_mfma_f32_16x16x32_f16 v[94:97], v[162:165], v[138:141], v[94:97]
	v_mfma_f32_16x16x32_f16 v[90:93], v[166:169], v[138:141], v[90:93]
	v_mfma_f32_16x16x32_f16 v[86:89], v[170:173], v[138:141], v[86:89]
	v_mfma_f32_16x16x32_f16 v[82:85], v[174:177], v[138:141], v[82:85]
	v_mfma_f32_16x16x32_f16 v[78:81], v[162:165], v[142:145], v[78:81]
	v_mfma_f32_16x16x32_f16 v[74:77], v[166:169], v[142:145], v[74:77]
	v_mfma_f32_16x16x32_f16 v[70:73], v[170:173], v[142:145], v[70:73]
	v_mfma_f32_16x16x32_f16 v[66:69], v[174:177], v[142:145], v[66:69]
	s_barrier
	ds_read_b128 v[146:149], v204 offset:8192
	ds_read_b128 v[150:153], v204 offset:10240
	ds_read_b128 v[154:157], v204 offset:12288
	ds_read_b128 v[158:161], v204 offset:14336
	s_add_i32 m0, s21, 0xc000
	s_add_u32 s40, s38, 0x40080
	s_addc_u32 s41, s39, 0
	global_load_lds_dwordx4 v1, s[40:41]
	s_add_i32 m0, s21, 0xe000
	s_add_u32 s40, s38, 0x60080
	s_addc_u32 s41, s39, 0
	global_load_lds_dwordx4 v1, s[40:41]
	s_waitcnt lgkmcnt(0)
	s_barrier
	v_mfma_f32_16x16x32_f16 v[62:65], v[162:165], v[146:149], v[62:65]
	v_mfma_f32_16x16x32_f16 v[58:61], v[166:169], v[146:149], v[58:61]
	v_mfma_f32_16x16x32_f16 v[54:57], v[170:173], v[146:149], v[54:57]
	v_mfma_f32_16x16x32_f16 v[50:53], v[174:177], v[146:149], v[50:53]
	v_mfma_f32_16x16x32_f16 v[46:49], v[162:165], v[150:153], v[46:49]
	v_mfma_f32_16x16x32_f16 v[42:45], v[166:169], v[150:153], v[42:45]
	v_mfma_f32_16x16x32_f16 v[38:41], v[170:173], v[150:153], v[38:41]
	v_mfma_f32_16x16x32_f16 v[34:37], v[174:177], v[150:153], v[34:37]
	v_mfma_f32_16x16x32_f16 v[30:33], v[162:165], v[154:157], v[30:33]
	v_mfma_f32_16x16x32_f16 v[26:29], v[166:169], v[154:157], v[26:29]
	v_mfma_f32_16x16x32_f16 v[22:25], v[170:173], v[154:157], v[22:25]
	v_mfma_f32_16x16x32_f16 v[18:21], v[174:177], v[154:157], v[18:21]
	v_mfma_f32_16x16x32_f16 v[14:17], v[162:165], v[158:161], v[14:17]
	v_mfma_f32_16x16x32_f16 v[10:13], v[166:169], v[158:161], v[10:13]
	v_mfma_f32_16x16x32_f16 v[6:9], v[170:173], v[158:161], v[6:9]
	v_mfma_f32_16x16x32_f16 v[2:5], v[174:177], v[158:161], v[2:5]
	s_barrier
	ds_read_b128 v[130:133], v205 offset:0
	ds_read_b128 v[134:137], v205 offset:2048
	ds_read_b128 v[138:141], v205 offset:4096
	ds_read_b128 v[142:145], v205 offset:6144
	ds_read_b128 v[162:165], v207 offset:32768
	ds_read_b128 v[166:169], v207 offset:34816
	ds_read_b128 v[170:173], v207 offset:36864
	ds_read_b128 v[174:177], v207 offset:38912
	s_add_i32 m0, s21, 0x2000
	s_add_u32 s40, s36, 0x20080
	s_addc_u32 s41, s37, 0
	global_load_lds_dwordx4 v1, s[40:41]
	s_add_i32 m0, s21, 0x6000
	s_add_u32 s40, s36, 0x60080
	s_addc_u32 s41, s37, 0
	global_load_lds_dwordx4 v1, s[40:41]
	s_waitcnt lgkmcnt(0)
	s_barrier
	v_mfma_f32_16x16x32_f16 v[126:129], v[162:165], v[130:133], v[126:129]
	v_mfma_f32_16x16x32_f16 v[122:125], v[166:169], v[130:133], v[122:125]
	v_mfma_f32_16x16x32_f16 v[118:121], v[170:173], v[130:133], v[118:121]
	v_mfma_f32_16x16x32_f16 v[114:117], v[174:177], v[130:133], v[114:117]
	v_mfma_f32_16x16x32_f16 v[110:113], v[162:165], v[134:137], v[110:113]
	v_mfma_f32_16x16x32_f16 v[106:109], v[166:169], v[134:137], v[106:109]
	v_mfma_f32_16x16x32_f16 v[102:105], v[170:173], v[134:137], v[102:105]
	v_mfma_f32_16x16x32_f16 v[98:101], v[174:177], v[134:137], v[98:101]
	v_mfma_f32_16x16x32_f16 v[94:97], v[162:165], v[138:141], v[94:97]
	v_mfma_f32_16x16x32_f16 v[90:93], v[166:169], v[138:141], v[90:93]
	v_mfma_f32_16x16x32_f16 v[86:89], v[170:173], v[138:141], v[86:89]
	v_mfma_f32_16x16x32_f16 v[82:85], v[174:177], v[138:141], v[82:85]
	v_mfma_f32_16x16x32_f16 v[78:81], v[162:165], v[142:145], v[78:81]
	v_mfma_f32_16x16x32_f16 v[74:77], v[166:169], v[142:145], v[74:77]
	v_mfma_f32_16x16x32_f16 v[70:73], v[170:173], v[142:145], v[70:73]
	v_mfma_f32_16x16x32_f16 v[66:69], v[174:177], v[142:145], v[66:69]
	s_barrier
	ds_read_b128 v[146:149], v205 offset:8192
	ds_read_b128 v[150:153], v205 offset:10240
	ds_read_b128 v[154:157], v205 offset:12288
	ds_read_b128 v[158:161], v205 offset:14336
	s_add_i32 m0, s21, 0x10000
	s_add_u32 s40, s36, 0x100
	s_addc_u32 s41, s37, 0
	global_load_lds_dwordx4 v1, s[40:41]
	s_add_i32 m0, s21, 0x18000
	s_add_u32 s40, s38, 0x100
	s_addc_u32 s41, s39, 0
	global_load_lds_dwordx4 v1, s[40:41]
	s_waitcnt vmcnt(4) lgkmcnt(0)
	s_barrier
	v_mfma_f32_16x16x32_f16 v[62:65], v[162:165], v[146:149], v[62:65]
	v_mfma_f32_16x16x32_f16 v[58:61], v[166:169], v[146:149], v[58:61]
	v_mfma_f32_16x16x32_f16 v[54:57], v[170:173], v[146:149], v[54:57]
	v_mfma_f32_16x16x32_f16 v[50:53], v[174:177], v[146:149], v[50:53]
	v_mfma_f32_16x16x32_f16 v[46:49], v[162:165], v[150:153], v[46:49]
	v_mfma_f32_16x16x32_f16 v[42:45], v[166:169], v[150:153], v[42:45]
	v_mfma_f32_16x16x32_f16 v[38:41], v[170:173], v[150:153], v[38:41]
	v_mfma_f32_16x16x32_f16 v[34:37], v[174:177], v[150:153], v[34:37]
	v_mfma_f32_16x16x32_f16 v[30:33], v[162:165], v[154:157], v[30:33]
	v_mfma_f32_16x16x32_f16 v[26:29], v[166:169], v[154:157], v[26:29]
	v_mfma_f32_16x16x32_f16 v[22:25], v[170:173], v[154:157], v[22:25]
	v_mfma_f32_16x16x32_f16 v[18:21], v[174:177], v[154:157], v[18:21]
	v_mfma_f32_16x16x32_f16 v[14:17], v[162:165], v[158:161], v[14:17]
	v_mfma_f32_16x16x32_f16 v[10:13], v[166:169], v[158:161], v[10:13]
	v_mfma_f32_16x16x32_f16 v[6:9], v[170:173], v[158:161], v[6:9]
	v_mfma_f32_16x16x32_f16 v[2:5], v[174:177], v[158:161], v[2:5]
	s_barrier
	s_add_u32 s36, s36, 0x80
	s_addc_u32 s37, s37, 0
	s_add_u32 s38, s38, 0x80
	s_addc_u32 s39, s39, 0
	s_add_i32 s23, s23, -1
	s_cmp_lg_u32 s23, 0
	s_cbranch_scc1 .Lp3_loop
	ds_read_b128 v[130:133], v200 offset:0
	ds_read_b128 v[134:137], v200 offset:2048
	ds_read_b128 v[138:141], v200 offset:4096
	ds_read_b128 v[142:145], v200 offset:6144
	ds_read_b128 v[162:165], v202 offset:32768
	ds_read_b128 v[166:169], v202 offset:34816
	ds_read_b128 v[170:173], v202 offset:36864
	ds_read_b128 v[174:177], v202 offset:38912
	s_add_i32 m0, s21, 0x14000
	s_add_u32 s40, s36, 0x40080
	s_addc_u32 s41, s37, 0
	global_load_lds_dwordx4 v1, s[40:41]
	s_add_i32 m0, s21, 0x1a000
	s_add_u32 s40, s38, 0x20080
	s_addc_u32 s41, s39, 0
	global_load_lds_dwordx4 v1, s[40:41]
	s_waitcnt vmcnt(4) lgkmcnt(0)
	s_barrier
	v_mfma_f32_16x16x32_f16 v[126:129], v[162:165], v[130:133], v[126:129]
	v_mfma_f32_16x16x32_f16 v[122:125], v[166:169], v[130:133], v[122:125]
	v_mfma_f32_16x16x32_f16 v[118:121], v[170:173], v[130:133], v[118:121]
	v_mfma_f32_16x16x32_f16 v[114:117], v[174:177], v[130:133], v[114:117]
	v_mfma_f32_16x16x32_f16 v[110:113], v[162:165], v[134:137], v[110:113]
	v_mfma_f32_16x16x32_f16 v[106:109], v[166:169], v[134:137], v[106:109]
	v_mfma_f32_16x16x32_f16 v[102:105], v[170:173], v[134:137], v[102:105]
	v_mfma_f32_16x16x32_f16 v[98:101], v[174:177], v[134:137], v[98:101]
	v_mfma_f32_16x16x32_f16 v[94:97], v[162:165], v[138:141], v[94:97]
	v_mfma_f32_16x16x32_f16 v[90:93], v[166:169], v[138:141], v[90:93]
	v_mfma_f32_16x16x32_f16 v[86:89], v[170:173], v[138:141], v[86:89]
	v_mfma_f32_16x16x32_f16 v[82:85], v[174:177], v[138:141], v[82:85]
	v_mfma_f32_16x16x32_f16 v[78:81], v[162:165], v[142:145], v[78:81]
	v_mfma_f32_16x16x32_f16 v[74:77], v[166:169], v[142:145], v[74:77]
	v_mfma_f32_16x16x32_f16 v[70:73], v[170:173], v[142:145], v[70:73]
	v_mfma_f32_16x16x32_f16 v[66:69], v[174:177], v[142:145], v[66:69]
	s_barrier
	ds_read_b128 v[146:149], v200 offset:8192
	ds_read_b128 v[150:153], v200 offset:10240
	ds_read_b128 v[154:157], v200 offset:12288
	ds_read_b128 v[158:161], v200 offset:14336
	s_add_i32 m0, s21, 0x1c000
	s_add_u32 s40, s38, 0x40080
	s_addc_u32 s41, s39, 0
	global_load_lds_dwordx4 v1, s[40:41]
	s_add_i32 m0, s21, 0x1e000
	s_add_u32 s40, s38, 0x60080
	s_addc_u32 s41, s39, 0
	global_load_lds_dwordx4 v1, s[40:41]
	s_waitcnt lgkmcnt(0)
	s_barrier
	v_mfma_f32_16x16x32_f16 v[62:65], v[162:165], v[146:149], v[62:65]
	v_mfma_f32_16x16x32_f16 v[58:61], v[166:169], v[146:149], v[58:61]
	v_mfma_f32_16x16x32_f16 v[54:57], v[170:173], v[146:149], v[54:57]
	v_mfma_f32_16x16x32_f16 v[50:53], v[174:177], v[146:149], v[50:53]
	v_mfma_f32_16x16x32_f16 v[46:49], v[162:165], v[150:153], v[46:49]
	v_mfma_f32_16x16x32_f16 v[42:45], v[166:169], v[150:153], v[42:45]
	v_mfma_f32_16x16x32_f16 v[38:41], v[170:173], v[150:153], v[38:41]
	v_mfma_f32_16x16x32_f16 v[34:37], v[174:177], v[150:153], v[34:37]
	v_mfma_f32_16x16x32_f16 v[30:33], v[162:165], v[154:157], v[30:33]
	v_mfma_f32_16x16x32_f16 v[26:29], v[166:169], v[154:157], v[26:29]
	v_mfma_f32_16x16x32_f16 v[22:25], v[170:173], v[154:157], v[22:25]
	v_mfma_f32_16x16x32_f16 v[18:21], v[174:177], v[154:157], v[18:21]
	v_mfma_f32_16x16x32_f16 v[14:17], v[162:165], v[158:161], v[14:17]
	v_mfma_f32_16x16x32_f16 v[10:13], v[166:169], v[158:161], v[10:13]
	v_mfma_f32_16x16x32_f16 v[6:9], v[170:173], v[158:161], v[6:9]
	v_mfma_f32_16x16x32_f16 v[2:5], v[174:177], v[158:161], v[2:5]
	s_barrier
	ds_read_b128 v[130:133], v201 offset:0
	ds_read_b128 v[134:137], v201 offset:2048
	ds_read_b128 v[138:141], v201 offset:4096
	ds_read_b128 v[142:145], v201 offset:6144
	ds_read_b128 v[162:165], v203 offset:32768
	ds_read_b128 v[166:169], v203 offset:34816
	ds_read_b128 v[170:173], v203 offset:36864
	ds_read_b128 v[174:177], v203 offset:38912
	s_add_i32 m0, s21, 0x12000
	s_add_u32 s40, s36, 0x20080
	s_addc_u32 s41, s37, 0
	global_load_lds_dwordx4 v1, s[40:41]
	s_add_i32 m0, s21, 0x16000
	s_add_u32 s40, s36, 0x60080
	s_addc_u32 s41, s37, 0
	global_load_lds_dwordx4 v1, s[40:41]
	s_waitcnt lgkmcnt(0)
	s_barrier
	v_mfma_f32_16x16x32_f16 v[126:129], v[162:165], v[130:133], v[126:129]
	v_mfma_f32_16x16x32_f16 v[122:125], v[166:169], v[130:133], v[122:125]
	v_mfma_f32_16x16x32_f16 v[118:121], v[170:173], v[130:133], v[118:121]
	v_mfma_f32_16x16x32_f16 v[114:117], v[174:177], v[130:133], v[114:117]
	v_mfma_f32_16x16x32_f16 v[110:113], v[162:165], v[134:137], v[110:113]
	v_mfma_f32_16x16x32_f16 v[106:109], v[166:169], v[134:137], v[106:109]
	v_mfma_f32_16x16x32_f16 v[102:105], v[170:173], v[134:137], v[102:105]
	v_mfma_f32_16x16x32_f16 v[98:101], v[174:177], v[134:137], v[98:101]
	v_mfma_f32_16x16x32_f16 v[94:97], v[162:165], v[138:141], v[94:97]
	v_mfma_f32_16x16x32_f16 v[90:93], v[166:169], v[138:141], v[90:93]
	v_mfma_f32_16x16x32_f16 v[86:89], v[170:173], v[138:141], v[86:89]
	v_mfma_f32_16x16x32_f16 v[82:85], v[174:177], v[138:141], v[82:85]
	v_mfma_f32_16x16x32_f16 v[78:81], v[162:165], v[142:145], v[78:81]
	v_mfma_f32_16x16x32_f16 v[74:77], v[166:169], v[142:145], v[74:77]
	v_mfma_f32_16x16x32_f16 v[70:73], v[170:173], v[142:145], v[70:73]
	v_mfma_f32_16x16x32_f16 v[66:69], v[174:177], v[142:145], v[66:69]
	s_barrier
	ds_read_b128 v[146:149], v201 offset:8192
	ds_read_b128 v[150:153], v201 offset:10240
	ds_read_b128 v[154:157], v201 offset:12288
	ds_read_b128 v[158:161], v201 offset:14336
	s_waitcnt vmcnt(2) lgkmcnt(0)
	s_barrier
	v_mfma_f32_16x16x32_f16 v[62:65], v[162:165], v[146:149], v[62:65]
	v_mfma_f32_16x16x32_f16 v[58:61], v[166:169], v[146:149], v[58:61]
	v_mfma_f32_16x16x32_f16 v[54:57], v[170:173], v[146:149], v[54:57]
	v_mfma_f32_16x16x32_f16 v[50:53], v[174:177], v[146:149], v[50:53]
	v_mfma_f32_16x16x32_f16 v[46:49], v[162:165], v[150:153], v[46:49]
	v_mfma_f32_16x16x32_f16 v[42:45], v[166:169], v[150:153], v[42:45]
	v_mfma_f32_16x16x32_f16 v[38:41], v[170:173], v[150:153], v[38:41]
	v_mfma_f32_16x16x32_f16 v[34:37], v[174:177], v[150:153], v[34:37]
	v_mfma_f32_16x16x32_f16 v[30:33], v[162:165], v[154:157], v[30:33]
	v_mfma_f32_16x16x32_f16 v[26:29], v[166:169], v[154:157], v[26:29]
	v_mfma_f32_16x16x32_f16 v[22:25], v[170:173], v[154:157], v[22:25]
	v_mfma_f32_16x16x32_f16 v[18:21], v[174:177], v[154:157], v[18:21]
	v_mfma_f32_16x16x32_f16 v[14:17], v[162:165], v[158:161], v[14:17]
	v_mfma_f32_16x16x32_f16 v[10:13], v[166:169], v[158:161], v[10:13]
	v_mfma_f32_16x16x32_f16 v[6:9], v[170:173], v[158:161], v[6:9]
	v_mfma_f32_16x16x32_f16 v[2:5], v[174:177], v[158:161], v[2:5]
	s_barrier
	s_add_u32 s36, s36, 0x80
	s_addc_u32 s37, s37, 0
	s_add_u32 s38, s38, 0x80
	s_addc_u32 s39, s39, 0
	ds_read_b128 v[130:133], v204 offset:0
	ds_read_b128 v[134:137], v204 offset:2048
	ds_read_b128 v[138:141], v204 offset:4096
	ds_read_b128 v[142:145], v204 offset:6144
	ds_read_b128 v[162:165], v206 offset:32768
	ds_read_b128 v[166:169], v206 offset:34816
	ds_read_b128 v[170:173], v206 offset:36864
	ds_read_b128 v[174:177], v206 offset:38912
	s_waitcnt vmcnt(0) lgkmcnt(0)
	s_barrier
	v_mfma_f32_16x16x32_f16 v[126:129], v[162:165], v[130:133], v[126:129]
	v_mfma_f32_16x16x32_f16 v[122:125], v[166:169], v[130:133], v[122:125]
	v_mfma_f32_16x16x32_f16 v[118:121], v[170:173], v[130:133], v[118:121]
	v_mfma_f32_16x16x32_f16 v[114:117], v[174:177], v[130:133], v[114:117]
	v_mfma_f32_16x16x32_f16 v[110:113], v[162:165], v[134:137], v[110:113]
	v_mfma_f32_16x16x32_f16 v[106:109], v[166:169], v[134:137], v[106:109]
	v_mfma_f32_16x16x32_f16 v[102:105], v[170:173], v[134:137], v[102:105]
	v_mfma_f32_16x16x32_f16 v[98:101], v[174:177], v[134:137], v[98:101]
	v_mfma_f32_16x16x32_f16 v[94:97], v[162:165], v[138:141], v[94:97]
	v_mfma_f32_16x16x32_f16 v[90:93], v[166:169], v[138:141], v[90:93]
	v_mfma_f32_16x16x32_f16 v[86:89], v[170:173], v[138:141], v[86:89]
	v_mfma_f32_16x16x32_f16 v[82:85], v[174:177], v[138:141], v[82:85]
	v_mfma_f32_16x16x32_f16 v[78:81], v[162:165], v[142:145], v[78:81]
	v_mfma_f32_16x16x32_f16 v[74:77], v[166:169], v[142:145], v[74:77]
	v_mfma_f32_16x16x32_f16 v[70:73], v[170:173], v[142:145], v[70:73]
	v_mfma_f32_16x16x32_f16 v[66:69], v[174:177], v[142:145], v[66:69]
	s_barrier
	ds_read_b128 v[146:149], v204 offset:8192
	ds_read_b128 v[150:153], v204 offset:10240
	ds_read_b128 v[154:157], v204 offset:12288
	ds_read_b128 v[158:161], v204 offset:14336
	s_waitcnt lgkmcnt(0)
	s_barrier
	v_mfma_f32_16x16x32_f16 v[62:65], v[162:165], v[146:149], v[62:65]
	v_mfma_f32_16x16x32_f16 v[58:61], v[166:169], v[146:149], v[58:61]
	v_mfma_f32_16x16x32_f16 v[54:57], v[170:173], v[146:149], v[54:57]
	v_mfma_f32_16x16x32_f16 v[50:53], v[174:177], v[146:149], v[50:53]
	v_mfma_f32_16x16x32_f16 v[46:49], v[162:165], v[150:153], v[46:49]
	v_mfma_f32_16x16x32_f16 v[42:45], v[166:169], v[150:153], v[42:45]
	v_mfma_f32_16x16x32_f16 v[38:41], v[170:173], v[150:153], v[38:41]
	v_mfma_f32_16x16x32_f16 v[34:37], v[174:177], v[150:153], v[34:37]
	v_mfma_f32_16x16x32_f16 v[30:33], v[162:165], v[154:157], v[30:33]
	v_mfma_f32_16x16x32_f16 v[26:29], v[166:169], v[154:157], v[26:29]
	v_mfma_f32_16x16x32_f16 v[22:25], v[170:173], v[154:157], v[22:25]
	v_mfma_f32_16x16x32_f16 v[18:21], v[174:177], v[154:157], v[18:21]
	v_mfma_f32_16x16x32_f16 v[14:17], v[162:165], v[158:161], v[14:17]
	v_mfma_f32_16x16x32_f16 v[10:13], v[166:169], v[158:161], v[10:13]
	v_mfma_f32_16x16x32_f16 v[6:9], v[170:173], v[158:161], v[6:9]
	v_mfma_f32_16x16x32_f16 v[2:5], v[174:177], v[158:161], v[2:5]
	s_barrier
	ds_read_b128 v[130:133], v205 offset:0
	ds_read_b128 v[134:137], v205 offset:2048
	ds_read_b128 v[138:141], v205 offset:4096
	ds_read_b128 v[142:145], v205 offset:6144
	ds_read_b128 v[162:165], v207 offset:32768
	ds_read_b128 v[166:169], v207 offset:34816
	ds_read_b128 v[170:173], v207 offset:36864
	ds_read_b128 v[174:177], v207 offset:38912
	s_waitcnt lgkmcnt(0)
	s_barrier
	v_mfma_f32_16x16x32_f16 v[126:129], v[162:165], v[130:133], v[126:129]
	v_mfma_f32_16x16x32_f16 v[122:125], v[166:169], v[130:133], v[122:125]
	v_mfma_f32_16x16x32_f16 v[118:121], v[170:173], v[130:133], v[118:121]
	v_mfma_f32_16x16x32_f16 v[114:117], v[174:177], v[130:133], v[114:117]
	v_mfma_f32_16x16x32_f16 v[110:113], v[162:165], v[134:137], v[110:113]
	v_mfma_f32_16x16x32_f16 v[106:109], v[166:169], v[134:137], v[106:109]
	v_mfma_f32_16x16x32_f16 v[102:105], v[170:173], v[134:137], v[102:105]
	v_mfma_f32_16x16x32_f16 v[98:101], v[174:177], v[134:137], v[98:101]
	v_mfma_f32_16x16x32_f16 v[94:97], v[162:165], v[138:141], v[94:97]
	v_mfma_f32_16x16x32_f16 v[90:93], v[166:169], v[138:141], v[90:93]
	v_mfma_f32_16x16x32_f16 v[86:89], v[170:173], v[138:141], v[86:89]
	v_mfma_f32_16x16x32_f16 v[82:85], v[174:177], v[138:141], v[82:85]
	v_mfma_f32_16x16x32_f16 v[78:81], v[162:165], v[142:145], v[78:81]
	v_mfma_f32_16x16x32_f16 v[74:77], v[166:169], v[142:145], v[74:77]
	v_mfma_f32_16x16x32_f16 v[70:73], v[170:173], v[142:145], v[70:73]
	v_mfma_f32_16x16x32_f16 v[66:69], v[174:177], v[142:145], v[66:69]
	s_barrier
	ds_read_b128 v[146:149], v205 offset:8192
	ds_read_b128 v[150:153], v205 offset:10240
	ds_read_b128 v[154:157], v205 offset:12288
	ds_read_b128 v[158:161], v205 offset:14336
	s_waitcnt lgkmcnt(0)
	s_barrier
	v_mfma_f32_16x16x32_f16 v[62:65], v[162:165], v[146:149], v[62:65]
	v_mfma_f32_16x16x32_f16 v[58:61], v[166:169], v[146:149], v[58:61]
	v_mfma_f32_16x16x32_f16 v[54:57], v[170:173], v[146:149], v[54:57]
	v_mfma_f32_16x16x32_f16 v[50:53], v[174:177], v[146:149], v[50:53]
	v_mfma_f32_16x16x32_f16 v[46:49], v[162:165], v[150:153], v[46:49]
	v_mfma_f32_16x16x32_f16 v[42:45], v[166:169], v[150:153], v[42:45]
	v_mfma_f32_16x16x32_f16 v[38:41], v[170:173], v[150:153], v[38:41]
	v_mfma_f32_16x16x32_f16 v[34:37], v[174:177], v[150:153], v[34:37]
	v_mfma_f32_16x16x32_f16 v[30:33], v[162:165], v[154:157], v[30:33]
	v_mfma_f32_16x16x32_f16 v[26:29], v[166:169], v[154:157], v[26:29]
	v_mfma_f32_16x16x32_f16 v[22:25], v[170:173], v[154:157], v[22:25]
	v_mfma_f32_16x16x32_f16 v[18:21], v[174:177], v[154:157], v[18:21]
	v_mfma_f32_16x16x32_f16 v[14:17], v[162:165], v[158:161], v[14:17]
	v_mfma_f32_16x16x32_f16 v[10:13], v[166:169], v[158:161], v[10:13]
	v_mfma_f32_16x16x32_f16 v[6:9], v[170:173], v[158:161], v[6:9]
	v_mfma_f32_16x16x32_f16 v[2:5], v[174:177], v[158:161], v[2:5]
	s_barrier
	s_cmp_eq_u32 s22, 1
	s_cbranch_scc1 .Lp3_skew1
	s_barrier
.Lp3_skew1:
	s_nop 7
	s_nop 1
	s_cmp_lt_u32 s20, 0x80
	v_readlane_b32 s4, v254, 55
	v_readlane_b32 s5, v254, 56
	v_readlane_b32 s2, v254, 12
	v_readlane_b32 s3, v254, 13
	s_cselect_b32 s46, s2, s4
	s_cselect_b32 s47, s3, s5
	s_cselect_b32 s42, s12, s10
	s_cselect_b32 s43, s13, s11
	s_and_b32 s2, s20, 0x7f
	s_lshl_b32 s2, s2, 20
	s_lshl_b32 s3, s19, 10
	s_add_i32 s2, s2, s3
	s_add_u32 s42, s42, s2
	s_addc_u32 s43, s43, 0
	s_add_u32 s46, s46, s2
	s_addc_u32 s47, s47, 0
	s_lshr_b32 s2, s20, 3
	s_cmp_lt_u32 s20, 0x80
	s_cselect_b32 s2, s2, 16
	s_add_i32 s2, s2, s54
	s_mul_i32 s2, s2, 0x6000
	s_add_i32 s2, s2, s3
	s_add_i32 s2, s2, 0x2000
	v_readlane_b32 s4, v254, 14
	v_readlane_b32 s5, v254, 15
	s_nop 3
	s_add_u32 s44, s4, s2
	s_addc_u32 s45, s5, 0
	v_and_b32_e32 v197, 15, v222
	v_lshrrev_b32_e32 v198, 8, v222
	v_lshl_or_b32 v197, v198, 7, v197
	v_bfe_u32 v198, v222, 6, 2
	v_bfe_u32 v199, v222, 4, 2
	v_lshlrev_b32_e32 v199, 4, v199
	v_lshl_or_b32 v196, v198, 8, v199
	v_lshl_or_b32 v194, v197, 12, v196
	v_mov_b32_e32 v195, v194
	global_load_dwordx4 v[178:181], v196, s[44:45] offset:0
	global_load_dwordx4 v[182:185], v196, s[44:45] offset:64
	global_load_dwordx4 v[186:189], v196, s[44:45] offset:128
	global_load_dwordx4 v[190:193], v196, s[44:45] offset:192
	global_load_dwordx4 v[130:133], v194, s[42:43] offset:0
	global_load_dwordx4 v[134:137], v194, s[42:43] offset:64
	global_load_dwordx4 v[138:141], v194, s[42:43] offset:128
	global_load_dwordx4 v[142:145], v194, s[42:43] offset:192
	v_add_u32_e32 v194, 0x10000, v194
	global_load_dwordx4 v[146:149], v194, s[42:43] offset:0
	global_load_dwordx4 v[150:153], v194, s[42:43] offset:64
	global_load_dwordx4 v[154:157], v194, s[42:43] offset:128
	global_load_dwordx4 v[158:161], v194, s[42:43] offset:192
	v_add_u32_e32 v194, 0x10000, v194
	global_load_dwordx4 v[162:165], v194, s[42:43] offset:0
	global_load_dwordx4 v[166:169], v194, s[42:43] offset:64
	global_load_dwordx4 v[170:173], v194, s[42:43] offset:128
	global_load_dwordx4 v[174:177], v194, s[42:43] offset:192
	v_add_u32_e32 v194, 0x10000, v194
	s_add_i32 s2, s29, s95
	s_cmp_lt_i32 s2, s53
	s_cselect_b32 s17, 1, 0
	s_cselect_b32 s29, s2, s29
	s_lshr_b32 s2, s29, 5
	s_lshl_b32 s2, s2, 3
	s_and_b32 s3, s29, 7
	s_add_i32 s20, s2, s3
	s_bfe_u32 s19, s29, 0x20003
	s_lshl_b32 s2, s20, 19
	s_add_u32 s36, s64, s2
	s_addc_u32 s37, s65, 0
	s_lshl_b32 s2, s19, 19
	s_add_u32 s38, s7, s2
	s_addc_u32 s39, s28, 0
	s_mov_b32 m0, s21
	s_nop 0
	global_load_lds_dwordx4 v1, s[36:37]
	s_add_i32 m0, s21, 0x2000
	s_add_u32 s40, s36, 0x20000
	s_addc_u32 s41, s37, 0
	global_load_lds_dwordx4 v1, s[40:41]
	s_add_i32 m0, s21, 0x4000
	s_add_u32 s40, s36, 0x40000
	s_addc_u32 s41, s37, 0
	global_load_lds_dwordx4 v1, s[40:41]
	s_add_i32 m0, s21, 0x6000
	s_add_u32 s40, s36, 0x60000
	s_addc_u32 s41, s37, 0
	global_load_lds_dwordx4 v1, s[40:41]
	s_add_i32 m0, s21, 0x8000
	s_nop 0
	global_load_lds_dwordx4 v1, s[38:39]
	s_add_i32 m0, s21, 0xa000
	s_add_u32 s40, s38, 0x20000
	s_addc_u32 s41, s39, 0
	global_load_lds_dwordx4 v1, s[40:41]
	s_add_i32 m0, s21, 0xc000
	s_add_u32 s40, s38, 0x40000
	s_addc_u32 s41, s39, 0
	global_load_lds_dwordx4 v1, s[40:41]
	s_add_i32 m0, s21, 0xe000
	s_add_u32 s40, s38, 0x60000
	s_addc_u32 s41, s39, 0
	global_load_lds_dwordx4 v1, s[40:41]
	s_waitcnt vmcnt(16)
	v_pk_fma_f32 v[126:127], v[126:127], v[178:179], v[130:131]
	v_pk_fma_f32 v[128:129], v[128:129], v[180:181], v[132:133]
	v_pk_fma_f32 v[122:123], v[122:123], v[182:183], v[134:135]
	v_pk_fma_f32 v[124:125], v[124:125], v[184:185], v[136:137]
	v_pk_fma_f32 v[118:119], v[118:119], v[186:187], v[138:139]
	v_pk_fma_f32 v[120:121], v[120:121], v[188:189], v[140:141]
	v_pk_fma_f32 v[114:115], v[114:115], v[190:191], v[142:143]
	v_pk_fma_f32 v[116:117], v[116:117], v[192:193], v[144:145]
	global_store_dwordx4 v195, v[126:129], s[46:47] offset:0
	global_store_dwordx4 v195, v[122:125], s[46:47] offset:64
	global_store_dwordx4 v195, v[118:121], s[46:47] offset:128
	global_store_dwordx4 v195, v[114:117], s[46:47] offset:192
	global_load_dwordx4 v[130:133], v194, s[42:43] offset:0
	global_load_dwordx4 v[134:137], v194, s[42:43] offset:64
	global_load_dwordx4 v[138:141], v194, s[42:43] offset:128
	global_load_dwordx4 v[142:145], v194, s[42:43] offset:192
	v_add_u32_e32 v194, 0x10000, v194
	s_waitcnt vmcnt(20)
	v_add_u32_e32 v195, 0x10000, v195
	v_pk_fma_f32 v[110:111], v[110:111], v[178:179], v[146:147]
	v_pk_fma_f32 v[112:113], v[112:113], v[180:181], v[148:149]
	v_pk_fma_f32 v[106:107], v[106:107], v[182:183], v[150:151]
	v_pk_fma_f32 v[108:109], v[108:109], v[184:185], v[152:153]
	v_pk_fma_f32 v[102:103], v[102:103], v[186:187], v[154:155]
	v_pk_fma_f32 v[104:105], v[104:105], v[188:189], v[156:157]
	v_pk_fma_f32 v[98:99], v[98:99], v[190:191], v[158:159]
	v_pk_fma_f32 v[100:101], v[100:101], v[192:193], v[160:161]
	global_store_dwordx4 v195, v[110:113], s[46:47] offset:0
	global_store_dwordx4 v195, v[106:109], s[46:47] offset:64
	global_store_dwordx4 v195, v[102:105], s[46:47] offset:128
	global_store_dwordx4 v195, v[98:101], s[46:47] offset:192
	global_load_dwordx4 v[146:149], v194, s[42:43] offset:0
	global_load_dwordx4 v[150:153], v194, s[42:43] offset:64
	global_load_dwordx4 v[154:157], v194, s[42:43] offset:128
	global_load_dwordx4 v[158:161], v194, s[42:43] offset:192
	v_add_u32_e32 v194, 0x10000, v194
	s_waitcnt vmcnt(24)
	v_add_u32_e32 v195, 0x10000, v195
	v_pk_fma_f32 v[94:95], v[94:95], v[178:179], v[162:163]
	v_pk_fma_f32 v[96:97], v[96:97], v[180:181], v[164:165]
	v_pk_fma_f32 v[90:91], v[90:91], v[182:183], v[166:167]
	v_pk_fma_f32 v[92:93], v[92:93], v[184:185], v[168:169]
	v_pk_fma_f32 v[86:87], v[86:87], v[186:187], v[170:171]
	v_pk_fma_f32 v[88:89], v[88:89], v[188:189], v[172:173]
	v_pk_fma_f32 v[82:83], v[82:83], v[190:191], v[174:175]
	v_pk_fma_f32 v[84:85], v[84:85], v[192:193], v[176:177]
	global_store_dwordx4 v195, v[94:97], s[46:47] offset:0
	global_store_dwordx4 v195, v[90:93], s[46:47] offset:64
	global_store_dwordx4 v195, v[86:89], s[46:47] offset:128
	global_store_dwordx4 v195, v[82:85], s[46:47] offset:192
	global_load_dwordx4 v[162:165], v194, s[42:43] offset:0
	global_load_dwordx4 v[166:169], v194, s[42:43] offset:64
	global_load_dwordx4 v[170:173], v194, s[42:43] offset:128
	global_load_dwordx4 v[174:177], v194, s[42:43] offset:192
	v_add_u32_e32 v194, 0x10000, v194
	s_waitcnt vmcnt(16)
	v_add_u32_e32 v195, 0x10000, v195
	v_pk_fma_f32 v[78:79], v[78:79], v[178:179], v[130:131]
	v_pk_fma_f32 v[80:81], v[80:81], v[180:181], v[132:133]
	v_pk_fma_f32 v[74:75], v[74:75], v[182:183], v[134:135]
	v_pk_fma_f32 v[76:77], v[76:77], v[184:185], v[136:137]
	v_pk_fma_f32 v[70:71], v[70:71], v[186:187], v[138:139]
	v_pk_fma_f32 v[72:73], v[72:73], v[188:189], v[140:141]
	v_pk_fma_f32 v[66:67], v[66:67], v[190:191], v[142:143]
	v_pk_fma_f32 v[68:69], v[68:69], v[192:193], v[144:145]
	global_store_dwordx4 v195, v[78:81], s[46:47] offset:0
	global_store_dwordx4 v195, v[74:77], s[46:47] offset:64
	global_store_dwordx4 v195, v[70:73], s[46:47] offset:128
	global_store_dwordx4 v195, v[66:69], s[46:47] offset:192
	global_load_dwordx4 v[130:133], v194, s[42:43] offset:0
	global_load_dwordx4 v[134:137], v194, s[42:43] offset:64
	global_load_dwordx4 v[138:141], v194, s[42:43] offset:128
	global_load_dwordx4 v[142:145], v194, s[42:43] offset:192
	v_add_u32_e32 v194, 0x10000, v194
	s_waitcnt vmcnt(16)
	v_add_u32_e32 v195, 0x10000, v195
	v_pk_fma_f32 v[62:63], v[62:63], v[178:179], v[146:147]
	v_pk_fma_f32 v[64:65], v[64:65], v[180:181], v[148:149]
	v_pk_fma_f32 v[58:59], v[58:59], v[182:183], v[150:151]
	v_pk_fma_f32 v[60:61], v[60:61], v[184:185], v[152:153]
	v_pk_fma_f32 v[54:55], v[54:55], v[186:187], v[154:155]
	v_pk_fma_f32 v[56:57], v[56:57], v[188:189], v[156:157]
	v_pk_fma_f32 v[50:51], v[50:51], v[190:191], v[158:159]
	v_pk_fma_f32 v[52:53], v[52:53], v[192:193], v[160:161]
	global_store_dwordx4 v195, v[62:65], s[46:47] offset:0
	global_store_dwordx4 v195, v[58:61], s[46:47] offset:64
	global_store_dwordx4 v195, v[54:57], s[46:47] offset:128
	global_store_dwordx4 v195, v[50:53], s[46:47] offset:192
	global_load_dwordx4 v[146:149], v194, s[42:43] offset:0
	global_load_dwordx4 v[150:153], v194, s[42:43] offset:64
	global_load_dwordx4 v[154:157], v194, s[42:43] offset:128
	global_load_dwordx4 v[158:161], v194, s[42:43] offset:192
	v_add_u32_e32 v194, 0x10000, v194
	s_waitcnt vmcnt(16)
	v_add_u32_e32 v195, 0x10000, v195
	v_pk_fma_f32 v[46:47], v[46:47], v[178:179], v[162:163]
	v_pk_fma_f32 v[48:49], v[48:49], v[180:181], v[164:165]
	v_pk_fma_f32 v[42:43], v[42:43], v[182:183], v[166:167]
	v_pk_fma_f32 v[44:45], v[44:45], v[184:185], v[168:169]
	v_pk_fma_f32 v[38:39], v[38:39], v[186:187], v[170:171]
	v_pk_fma_f32 v[40:41], v[40:41], v[188:189], v[172:173]
	v_pk_fma_f32 v[34:35], v[34:35], v[190:191], v[174:175]
	v_pk_fma_f32 v[36:37], v[36:37], v[192:193], v[176:177]
	global_store_dwordx4 v195, v[46:49], s[46:47] offset:0
	global_store_dwordx4 v195, v[42:45], s[46:47] offset:64
	global_store_dwordx4 v195, v[38:41], s[46:47] offset:128
	global_store_dwordx4 v195, v[34:37], s[46:47] offset:192
	s_waitcnt vmcnt(12)
	v_add_u32_e32 v195, 0x10000, v195
	v_pk_fma_f32 v[30:31], v[30:31], v[178:179], v[130:131]
	v_pk_fma_f32 v[32:33], v[32:33], v[180:181], v[132:133]
	v_pk_fma_f32 v[26:27], v[26:27], v[182:183], v[134:135]
	v_pk_fma_f32 v[28:29], v[28:29], v[184:185], v[136:137]
	v_pk_fma_f32 v[22:23], v[22:23], v[186:187], v[138:139]
	v_pk_fma_f32 v[24:25], v[24:25], v[188:189], v[140:141]
	v_pk_fma_f32 v[18:19], v[18:19], v[190:191], v[142:143]
	v_pk_fma_f32 v[20:21], v[20:21], v[192:193], v[144:145]
	global_store_dwordx4 v195, v[30:33], s[46:47] offset:0
	global_store_dwordx4 v195, v[26:29], s[46:47] offset:64
	global_store_dwordx4 v195, v[22:25], s[46:47] offset:128
	global_store_dwordx4 v195, v[18:21], s[46:47] offset:192
	s_waitcnt vmcnt(8)
	v_add_u32_e32 v195, 0x10000, v195
	v_pk_fma_f32 v[14:15], v[14:15], v[178:179], v[146:147]
	v_pk_fma_f32 v[16:17], v[16:17], v[180:181], v[148:149]
	v_pk_fma_f32 v[10:11], v[10:11], v[182:183], v[150:151]
	v_pk_fma_f32 v[12:13], v[12:13], v[184:185], v[152:153]
	v_pk_fma_f32 v[6:7], v[6:7], v[186:187], v[154:155]
	v_pk_fma_f32 v[8:9], v[8:9], v[188:189], v[156:157]
	v_pk_fma_f32 v[2:3], v[2:3], v[190:191], v[158:159]
	v_pk_fma_f32 v[4:5], v[4:5], v[192:193], v[160:161]
	global_store_dwordx4 v195, v[14:17], s[46:47] offset:0
	global_store_dwordx4 v195, v[10:13], s[46:47] offset:64
	global_store_dwordx4 v195, v[6:9], s[46:47] offset:128
	global_store_dwordx4 v195, v[2:5], s[46:47] offset:192
	s_cmp_lg_u32 s17, 0
	s_cbranch_scc1 .Lp3_cont
	v_readlane_b32 s36, v254, 0
	v_readlane_b32 s37, v254, 1
	v_readlane_b32 s38, v254, 2
	v_readlane_b32 s39, v254, 3
	v_readlane_b32 s40, v254, 4
	v_readlane_b32 s41, v254, 5
	v_readlane_b32 s42, v254, 6
	v_readlane_b32 s43, v254, 7
	v_readlane_b32 s44, v254, 8
	v_readlane_b32 s45, v254, 9
	v_readlane_b32 s46, v254, 10
	v_readlane_b32 s47, v254, 11
	v_readlane_b32 s48, v254, 12
	v_readlane_b32 s49, v254, 13
	v_readlane_b32 s50, v254, 14
	v_readlane_b32 s51, v254, 15
	v_readlane_b32 s4, v254, 55
	v_readlane_b32 s5, v254, 56
	s_mov_b64 s[16:17], s[48:49]
	s_mov_b64 s[18:19], s[50:51]
	s_mov_b64 s[2:3], 0x2000
	s_add_i32 s29, s29, s95
	s_branch .LBB0_1064

.LBB0_1146:
	s_lshr_b32 s2, s18, 5
	s_lshl_b32 s2, s2, 3
	s_and_b32 s3, s18, 7
	s_add_i32 s20, s2, s3
	s_bfe_u32 s19, s18, 0x20003
	s_mul_i32 s2, s20, 0x160000
	s_add_u32 s36, s96, s2
	s_addc_u32 s37, s97, 0
	s_mul_i32 s2, s19, 0x160000
	s_add_u32 s38, s16, s2
	s_addc_u32 s39, s17, 0
	v_lshrrev_b32_e32 v194, 3, v222
	v_lshrrev_b32_e32 v195, 4, v222
	v_xor_b32_e32 v195, v195, v222
	v_and_b32_e32 v195, 7, v195
	v_lshlrev_b32_e32 v195, 4, v195
	v_mul_u32_u24_e32 v194, 0x1600, v194
	v_add_u32_e32 v1, v194, v195
	v_readfirstlane_b32 s21, v222
	s_nop 3
	s_lshr_b32 s22, s21, 8
	s_lshr_b32 s21, s21, 6
	s_lshl_b32 s21, s21, 10
	s_barrier
	s_mov_b32 m0, s21
	s_nop 0
	global_load_lds_dwordx4 v1, s[36:37]
	s_add_i32 m0, s21, 0x2000
	s_add_u32 s40, s36, 0x58000
	s_addc_u32 s41, s37, 0
	global_load_lds_dwordx4 v1, s[40:41]
	s_add_i32 m0, s21, 0x4000
	s_add_u32 s40, s36, 0xb0000
	s_addc_u32 s41, s37, 0
	global_load_lds_dwordx4 v1, s[40:41]
	s_add_i32 m0, s21, 0x6000
	s_add_u32 s40, s36, 0x108000
	s_addc_u32 s41, s37, 0
	global_load_lds_dwordx4 v1, s[40:41]
	s_add_i32 m0, s21, 0x8000
	s_nop 0
	global_load_lds_dwordx4 v1, s[38:39]
	s_add_i32 m0, s21, 0xa000
	s_add_u32 s40, s38, 0x58000
	s_addc_u32 s41, s39, 0
	global_load_lds_dwordx4 v1, s[40:41]
	s_add_i32 m0, s21, 0xc000
	s_add_u32 s40, s38, 0xb0000
	s_addc_u32 s41, s39, 0
	global_load_lds_dwordx4 v1, s[40:41]
	s_add_i32 m0, s21, 0xe000
	s_add_u32 s40, s38, 0x108000
	s_addc_u32 s41, s39, 0
	global_load_lds_dwordx4 v1, s[40:41]
	s_waitcnt vmcnt(0)

.Lp5_skew0:
	ds_read_b128 v[130:133], v200 offset:0
	ds_read_b128 v[134:137], v200 offset:2048
	ds_read_b128 v[138:141], v200 offset:4096
	ds_read_b128 v[142:145], v200 offset:6144
	ds_read_b128 v[162:165], v202 offset:32768
	ds_read_b128 v[166:169], v202 offset:34816
	ds_read_b128 v[170:173], v202 offset:36864
	ds_read_b128 v[174:177], v202 offset:38912
	s_add_i32 m0, s21, 0x14000
	s_add_u32 s40, s36, 0xb0080
	s_addc_u32 s41, s37, 0
	global_load_lds_dwordx4 v1, s[40:41]
	s_add_i32 m0, s21, 0x1a000
	s_add_u32 s40, s38, 0x58080
	s_addc_u32 s41, s39, 0
	global_load_lds_dwordx4 v1, s[40:41]
	s_waitcnt lgkmcnt(0)
	s_barrier
	v_mfma_f32_16x16x32_f16 v[126:129], v[162:165], v[130:133], 0
	v_mfma_f32_16x16x32_f16 v[122:125], v[166:169], v[130:133], 0
	v_mfma_f32_16x16x32_f16 v[118:121], v[170:173], v[130:133], 0
	v_mfma_f32_16x16x32_f16 v[114:117], v[174:177], v[130:133], 0
	v_mfma_f32_16x16x32_f16 v[110:113], v[162:165], v[134:137], 0
	v_mfma_f32_16x16x32_f16 v[106:109], v[166:169], v[134:137], 0
	v_mfma_f32_16x16x32_f16 v[102:105], v[170:173], v[134:137], 0
	v_mfma_f32_16x16x32_f16 v[98:101], v[174:177], v[134:137], 0
	v_mfma_f32_16x16x32_f16 v[94:97], v[162:165], v[138:141], 0
	v_mfma_f32_16x16x32_f16 v[90:93], v[166:169], v[138:141], 0
	v_mfma_f32_16x16x32_f16 v[86:89], v[170:173], v[138:141], 0
	v_mfma_f32_16x16x32_f16 v[82:85], v[174:177], v[138:141], 0
	v_mfma_f32_16x16x32_f16 v[78:81], v[162:165], v[142:145], 0
	v_mfma_f32_16x16x32_f16 v[74:77], v[166:169], v[142:145], 0
	v_mfma_f32_16x16x32_f16 v[70:73], v[170:173], v[142:145], 0
	v_mfma_f32_16x16x32_f16 v[66:69], v[174:177], v[142:145], 0
	s_barrier
	ds_read_b128 v[146:149], v200 offset:8192
	ds_read_b128 v[150:153], v200 offset:10240
	ds_read_b128 v[154:157], v200 offset:12288
	ds_read_b128 v[158:161], v200 offset:14336
	s_add_i32 m0, s21, 0x1c000
	s_add_u32 s40, s38, 0xb0080
	s_addc_u32 s41, s39, 0
	global_load_lds_dwordx4 v1, s[40:41]
	s_add_i32 m0, s21, 0x1e000
	s_add_u32 s40, s38, 0x108080
	s_addc_u32 s41, s39, 0
	global_load_lds_dwordx4 v1, s[40:41]
	s_waitcnt lgkmcnt(0)
	s_barrier
	v_mfma_f32_16x16x32_f16 v[62:65], v[162:165], v[146:149], 0
	v_mfma_f32_16x16x32_f16 v[58:61], v[166:169], v[146:149], 0
	v_mfma_f32_16x16x32_f16 v[54:57], v[170:173], v[146:149], 0
	v_mfma_f32_16x16x32_f16 v[50:53], v[174:177], v[146:149], 0
	v_mfma_f32_16x16x32_f16 v[46:49], v[162:165], v[150:153], 0
	v_mfma_f32_16x16x32_f16 v[42:45], v[166:169], v[150:153], 0
	v_mfma_f32_16x16x32_f16 v[38:41], v[170:173], v[150:153], 0
	v_mfma_f32_16x16x32_f16 v[34:37], v[174:177], v[150:153], 0
	v_mfma_f32_16x16x32_f16 v[30:33], v[162:165], v[154:157], 0
	v_mfma_f32_16x16x32_f16 v[26:29], v[166:169], v[154:157], 0
	v_mfma_f32_16x16x32_f16 v[22:25], v[170:173], v[154:157], 0
	v_mfma_f32_16x16x32_f16 v[18:21], v[174:177], v[154:157], 0
	v_mfma_f32_16x16x32_f16 v[14:17], v[162:165], v[158:161], 0
	v_mfma_f32_16x16x32_f16 v[10:13], v[166:169], v[158:161], 0
	v_mfma_f32_16x16x32_f16 v[6:9], v[170:173], v[158:161], 0
	v_mfma_f32_16x16x32_f16 v[2:5], v[174:177], v[158:161], 0
	s_barrier
	ds_read_b128 v[130:133], v201 offset:0
	ds_read_b128 v[134:137], v201 offset:2048
	ds_read_b128 v[138:141], v201 offset:4096
	ds_read_b128 v[142:145], v201 offset:6144
	ds_read_b128 v[162:165], v203 offset:32768
	ds_read_b128 v[166:169], v203 offset:34816
	ds_read_b128 v[170:173], v203 offset:36864
	ds_read_b128 v[174:177], v203 offset:38912
	s_add_i32 m0, s21, 0x12000
	s_add_u32 s40, s36, 0x58080
	s_addc_u32 s41, s37, 0
	global_load_lds_dwordx4 v1, s[40:41]
	s_add_i32 m0, s21, 0x16000
	s_add_u32 s40, s36, 0x108080
	s_addc_u32 s41, s37, 0
	global_load_lds_dwordx4 v1, s[40:41]
	s_waitcnt lgkmcnt(0)
	s_barrier
	v_mfma_f32_16x16x32_f16 v[126:129], v[162:165], v[130:133], v[126:129]
	v_mfma_f32_16x16x32_f16 v[122:125], v[166:169], v[130:133], v[122:125]
	v_mfma_f32_16x16x32_f16 v[118:121], v[170:173], v[130:133], v[118:121]
	v_mfma_f32_16x16x32_f16 v[114:117], v[174:177], v[130:133], v[114:117]
	v_mfma_f32_16x16x32_f16 v[110:113], v[162:165], v[134:137], v[110:113]
	v_mfma_f32_16x16x32_f16 v[106:109], v[166:169], v[134:137], v[106:109]
	v_mfma_f32_16x16x32_f16 v[102:105], v[170:173], v[134:137], v[102:105]
	v_mfma_f32_16x16x32_f16 v[98:101], v[174:177], v[134:137], v[98:101]
	v_mfma_f32_16x16x32_f16 v[94:97], v[162:165], v[138:141], v[94:97]
	v_mfma_f32_16x16x32_f16 v[90:93], v[166:169], v[138:141], v[90:93]
	v_mfma_f32_16x16x32_f16 v[86:89], v[170:173], v[138:141], v[86:89]
	v_mfma_f32_16x16x32_f16 v[82:85], v[174:177], v[138:141], v[82:85]
	v_mfma_f32_16x16x32_f16 v[78:81], v[162:165], v[142:145], v[78:81]
	v_mfma_f32_16x16x32_f16 v[74:77], v[166:169], v[142:145], v[74:77]
	v_mfma_f32_16x16x32_f16 v[70:73], v[170:173], v[142:145], v[70:73]
	v_mfma_f32_16x16x32_f16 v[66:69], v[174:177], v[142:145], v[66:69]
	s_barrier
	ds_read_b128 v[146:149], v201 offset:8192
	ds_read_b128 v[150:153], v201 offset:10240
	ds_read_b128 v[154:157], v201 offset:12288
	ds_read_b128 v[158:161], v201 offset:14336
	s_mov_b32 m0, s21
	s_add_u32 s40, s36, 0x100
	s_addc_u32 s41, s37, 0
	global_load_lds_dwordx4 v1, s[40:41]
	s_add_i32 m0, s21, 0x8000
	s_add_u32 s40, s38, 0x100
	s_addc_u32 s41, s39, 0
	global_load_lds_dwordx4 v1, s[40:41]
	s_waitcnt vmcnt(4) lgkmcnt(0)
	s_barrier
	v_mfma_f32_16x16x32_f16 v[62:65], v[162:165], v[146:149], v[62:65]
	v_mfma_f32_16x16x32_f16 v[58:61], v[166:169], v[146:149], v[58:61]
	v_mfma_f32_16x16x32_f16 v[54:57], v[170:173], v[146:149], v[54:57]
	v_mfma_f32_16x16x32_f16 v[50:53], v[174:177], v[146:149], v[50:53]
	v_mfma_f32_16x16x32_f16 v[46:49], v[162:165], v[150:153], v[46:49]
	v_mfma_f32_16x16x32_f16 v[42:45], v[166:169], v[150:153], v[42:45]
	v_mfma_f32_16x16x32_f16 v[38:41], v[170:173], v[150:153], v[38:41]
	v_mfma_f32_16x16x32_f16 v[34:37], v[174:177], v[150:153], v[34:37]
	v_mfma_f32_16x16x32_f16 v[30:33], v[162:165], v[154:157], v[30:33]
	v_mfma_f32_16x16x32_f16 v[26:29], v[166:169], v[154:157], v[26:29]
	v_mfma_f32_16x16x32_f16 v[22:25], v[170:173], v[154:157], v[22:25]
	v_mfma_f32_16x16x32_f16 v[18:21], v[174:177], v[154:157], v[18:21]
	v_mfma_f32_16x16x32_f16 v[14:17], v[162:165], v[158:161], v[14:17]
	v_mfma_f32_16x16x32_f16 v[10:13], v[166:169], v[158:161], v[10:13]
	v_mfma_f32_16x16x32_f16 v[6:9], v[170:173], v[158:161], v[6:9]
	v_mfma_f32_16x16x32_f16 v[2:5], v[174:177], v[158:161], v[2:5]
	s_barrier
	s_add_u32 s36, s36, 0x80
	s_addc_u32 s37, s37, 0
	s_add_u32 s38, s38, 0x80
	s_addc_u32 s39, s39, 0
	ds_read_b128 v[130:133], v204 offset:0
	ds_read_b128 v[134:137], v204 offset:2048
	ds_read_b128 v[138:141], v204 offset:4096
	ds_read_b128 v[142:145], v204 offset:6144
	ds_read_b128 v[162:165], v206 offset:32768
	ds_read_b128 v[166:169], v206 offset:34816
	ds_read_b128 v[170:173], v206 offset:36864
	ds_read_b128 v[174:177], v206 offset:38912
	s_add_i32 m0, s21, 0x4000
	s_add_u32 s40, s36, 0xb0080
	s_addc_u32 s41, s37, 0
	global_load_lds_dwordx4 v1, s[40:41]
	s_add_i32 m0, s21, 0xa000
	s_add_u32 s40, s38, 0x58080
	s_addc_u32 s41, s39, 0
	global_load_lds_dwordx4 v1, s[40:41]
	s_waitcnt vmcnt(4) lgkmcnt(0)
	s_barrier
	v_mfma_f32_16x16x32_f16 v[126:129], v[162:165], v[130:133], v[126:129]
	v_mfma_f32_16x16x32_f16 v[122:125], v[166:169], v[130:133], v[122:125]
	v_mfma_f32_16x16x32_f16 v[118:121], v[170:173], v[130:133], v[118:121]
	v_mfma_f32_16x16x32_f16 v[114:117], v[174:177], v[130:133], v[114:117]
	v_mfma_f32_16x16x32_f16 v[110:113], v[162:165], v[134:137], v[110:113]
	v_mfma_f32_16x16x32_f16 v[106:109], v[166:169], v[134:137], v[106:109]
	v_mfma_f32_16x16x32_f16 v[102:105], v[170:173], v[134:137], v[102:105]
	v_mfma_f32_16x16x32_f16 v[98:101], v[174:177], v[134:137], v[98:101]
	v_mfma_f32_16x16x32_f16 v[94:97], v[162:165], v[138:141], v[94:97]
	v_mfma_f32_16x16x32_f16 v[90:93], v[166:169], v[138:141], v[90:93]
	v_mfma_f32_16x16x32_f16 v[86:89], v[170:173], v[138:141], v[86:89]
	v_mfma_f32_16x16x32_f16 v[82:85], v[174:177], v[138:141], v[82:85]
	v_mfma_f32_16x16x32_f16 v[78:81], v[162:165], v[142:145], v[78:81]
	v_mfma_f32_16x16x32_f16 v[74:77], v[166:169], v[142:145], v[74:77]
	v_mfma_f32_16x16x32_f16 v[70:73], v[170:173], v[142:145], v[70:73]
	v_mfma_f32_16x16x32_f16 v[66:69], v[174:177], v[142:145], v[66:69]
	s_barrier
	ds_read_b128 v[146:149], v204 offset:8192
	ds_read_b128 v[150:153], v204 offset:10240
	ds_read_b128 v[154:157], v204 offset:12288
	ds_read_b128 v[158:161], v204 offset:14336
	s_add_i32 m0, s21, 0xc000
	s_add_u32 s40, s38, 0xb0080
	s_addc_u32 s41, s39, 0
	global_load_lds_dwordx4 v1, s[40:41]
	s_add_i32 m0, s21, 0xe000
	s_add_u32 s40, s38, 0x108080
	s_addc_u32 s41, s39, 0
	global_load_lds_dwordx4 v1, s[40:41]
	s_waitcnt lgkmcnt(0)
	s_barrier
	v_mfma_f32_16x16x32_f16 v[62:65], v[162:165], v[146:149], v[62:65]
	v_mfma_f32_16x16x32_f16 v[58:61], v[166:169], v[146:149], v[58:61]
	v_mfma_f32_16x16x32_f16 v[54:57], v[170:173], v[146:149], v[54:57]
	v_mfma_f32_16x16x32_f16 v[50:53], v[174:177], v[146:149], v[50:53]
	v_mfma_f32_16x16x32_f16 v[46:49], v[162:165], v[150:153], v[46:49]
	v_mfma_f32_16x16x32_f16 v[42:45], v[166:169], v[150:153], v[42:45]
	v_mfma_f32_16x16x32_f16 v[38:41], v[170:173], v[150:153], v[38:41]
	v_mfma_f32_16x16x32_f16 v[34:37], v[174:177], v[150:153], v[34:37]
	v_mfma_f32_16x16x32_f16 v[30:33], v[162:165], v[154:157], v[30:33]
	v_mfma_f32_16x16x32_f16 v[26:29], v[166:169], v[154:157], v[26:29]
	v_mfma_f32_16x16x32_f16 v[22:25], v[170:173], v[154:157], v[22:25]
	v_mfma_f32_16x16x32_f16 v[18:21], v[174:177], v[154:157], v[18:21]
	v_mfma_f32_16x16x32_f16 v[14:17], v[162:165], v[158:161], v[14:17]
	v_mfma_f32_16x16x32_f16 v[10:13], v[166:169], v[158:161], v[10:13]
	v_mfma_f32_16x16x32_f16 v[6:9], v[170:173], v[158:161], v[6:9]
	v_mfma_f32_16x16x32_f16 v[2:5], v[174:177], v[158:161], v[2:5]
	s_barrier
	ds_read_b128 v[130:133], v205 offset:0
	ds_read_b128 v[134:137], v205 offset:2048
	ds_read_b128 v[138:141], v205 offset:4096
	ds_read_b128 v[142:145], v205 offset:6144
	ds_read_b128 v[162:165], v207 offset:32768
	ds_read_b128 v[166:169], v207 offset:34816
	ds_read_b128 v[170:173], v207 offset:36864
	ds_read_b128 v[174:177], v207 offset:38912
	s_add_i32 m0, s21, 0x2000
	s_add_u32 s40, s36, 0x58080
	s_addc_u32 s41, s37, 0
	global_load_lds_dwordx4 v1, s[40:41]
	s_add_i32 m0, s21, 0x6000
	s_add_u32 s40, s36, 0x108080
	s_addc_u32 s41, s37, 0
	global_load_lds_dwordx4 v1, s[40:41]
	s_waitcnt lgkmcnt(0)
	s_barrier
	v_mfma_f32_16x16x32_f16 v[126:129], v[162:165], v[130:133], v[126:129]
	v_mfma_f32_16x16x32_f16 v[122:125], v[166:169], v[130:133], v[122:125]
	v_mfma_f32_16x16x32_f16 v[118:121], v[170:173], v[130:133], v[118:121]
	v_mfma_f32_16x16x32_f16 v[114:117], v[174:177], v[130:133], v[114:117]
	v_mfma_f32_16x16x32_f16 v[110:113], v[162:165], v[134:137], v[110:113]
	v_mfma_f32_16x16x32_f16 v[106:109], v[166:169], v[134:137], v[106:109]
	v_mfma_f32_16x16x32_f16 v[102:105], v[170:173], v[134:137], v[102:105]
	v_mfma_f32_16x16x32_f16 v[98:101], v[174:177], v[134:137], v[98:101]
	v_mfma_f32_16x16x32_f16 v[94:97], v[162:165], v[138:141], v[94:97]
	v_mfma_f32_16x16x32_f16 v[90:93], v[166:169], v[138:141], v[90:93]
	v_mfma_f32_16x16x32_f16 v[86:89], v[170:173], v[138:141], v[86:89]
	v_mfma_f32_16x16x32_f16 v[82:85], v[174:177], v[138:141], v[82:85]
	v_mfma_f32_16x16x32_f16 v[78:81], v[162:165], v[142:145], v[78:81]
	v_mfma_f32_16x16x32_f16 v[74:77], v[166:169], v[142:145], v[74:77]
	v_mfma_f32_16x16x32_f16 v[70:73], v[170:173], v[142:145], v[70:73]
	v_mfma_f32_16x16x32_f16 v[66:69], v[174:177], v[142:145], v[66:69]
	s_barrier
	ds_read_b128 v[146:149], v205 offset:8192
	ds_read_b128 v[150:153], v205 offset:10240
	ds_read_b128 v[154:157], v205 offset:12288
	ds_read_b128 v[158:161], v205 offset:14336
	s_add_i32 m0, s21, 0x10000
	s_add_u32 s40, s36, 0x100
	s_addc_u32 s41, s37, 0
	global_load_lds_dwordx4 v1, s[40:41]
	s_add_i32 m0, s21, 0x18000
	s_add_u32 s40, s38, 0x100
	s_addc_u32 s41, s39, 0
	global_load_lds_dwordx4 v1, s[40:41]
	s_waitcnt vmcnt(4) lgkmcnt(0)
	s_barrier
	v_mfma_f32_16x16x32_f16 v[62:65], v[162:165], v[146:149], v[62:65]
	v_mfma_f32_16x16x32_f16 v[58:61], v[166:169], v[146:149], v[58:61]
	v_mfma_f32_16x16x32_f16 v[54:57], v[170:173], v[146:149], v[54:57]
	v_mfma_f32_16x16x32_f16 v[50:53], v[174:177], v[146:149], v[50:53]
	v_mfma_f32_16x16x32_f16 v[46:49], v[162:165], v[150:153], v[46:49]
	v_mfma_f32_16x16x32_f16 v[42:45], v[166:169], v[150:153], v[42:45]
	v_mfma_f32_16x16x32_f16 v[38:41], v[170:173], v[150:153], v[38:41]
	v_mfma_f32_16x16x32_f16 v[34:37], v[174:177], v[150:153], v[34:37]
	v_mfma_f32_16x16x32_f16 v[30:33], v[162:165], v[154:157], v[30:33]
	v_mfma_f32_16x16x32_f16 v[26:29], v[166:169], v[154:157], v[26:29]
	v_mfma_f32_16x16x32_f16 v[22:25], v[170:173], v[154:157], v[22:25]
	v_mfma_f32_16x16x32_f16 v[18:21], v[174:177], v[154:157], v[18:21]
	v_mfma_f32_16x16x32_f16 v[14:17], v[162:165], v[158:161], v[14:17]
	v_mfma_f32_16x16x32_f16 v[10:13], v[166:169], v[158:161], v[10:13]
	v_mfma_f32_16x16x32_f16 v[6:9], v[170:173], v[158:161], v[6:9]
	v_mfma_f32_16x16x32_f16 v[2:5], v[174:177], v[158:161], v[2:5]
	s_barrier
	s_add_u32 s36, s36, 0x80
	s_addc_u32 s37, s37, 0
	s_add_u32 s38, s38, 0x80
	s_addc_u32 s39, s39, 0
	s_movk_i32 s23, 20
.Lp5_loop:
	ds_read_b128 v[130:133], v200 offset:0
	ds_read_b128 v[134:137], v200 offset:2048
	ds_read_b128 v[138:141], v200 offset:4096
	ds_read_b128 v[142:145], v200 offset:6144
	ds_read_b128 v[162:165], v202 offset:32768
	ds_read_b128 v[166:169], v202 offset:34816
	ds_read_b128 v[170:173], v202 offset:36864
	ds_read_b128 v[174:177], v202 offset:38912
	s_add_i32 m0, s21, 0x14000
	s_add_u32 s40, s36, 0xb0080
	s_addc_u32 s41, s37, 0
	global_load_lds_dwordx4 v1, s[40:41]
	s_add_i32 m0, s21, 0x1a000
	s_add_u32 s40, s38, 0x58080
	s_addc_u32 s41, s39, 0
	global_load_lds_dwordx4 v1, s[40:41]
	s_waitcnt vmcnt(4) lgkmcnt(0)
	s_barrier
	v_mfma_f32_16x16x32_f16 v[126:129], v[162:165], v[130:133], v[126:129]
	v_mfma_f32_16x16x32_f16 v[122:125], v[166:169], v[130:133], v[122:125]
	v_mfma_f32_16x16x32_f16 v[118:121], v[170:173], v[130:133], v[118:121]
	v_mfma_f32_16x16x32_f16 v[114:117], v[174:177], v[130:133], v[114:117]
	v_mfma_f32_16x16x32_f16 v[110:113], v[162:165], v[134:137], v[110:113]
	v_mfma_f32_16x16x32_f16 v[106:109], v[166:169], v[134:137], v[106:109]
	v_mfma_f32_16x16x32_f16 v[102:105], v[170:173], v[134:137], v[102:105]
	v_mfma_f32_16x16x32_f16 v[98:101], v[174:177], v[134:137], v[98:101]
	v_mfma_f32_16x16x32_f16 v[94:97], v[162:165], v[138:141], v[94:97]
	v_mfma_f32_16x16x32_f16 v[90:93], v[166:169], v[138:141], v[90:93]
	v_mfma_f32_16x16x32_f16 v[86:89], v[170:173], v[138:141], v[86:89]
	v_mfma_f32_16x16x32_f16 v[82:85], v[174:177], v[138:141], v[82:85]
	v_mfma_f32_16x16x32_f16 v[78:81], v[162:165], v[142:145], v[78:81]
	v_mfma_f32_16x16x32_f16 v[74:77], v[166:169], v[142:145], v[74:77]
	v_mfma_f32_16x16x32_f16 v[70:73], v[170:173], v[142:145], v[70:73]
	v_mfma_f32_16x16x32_f16 v[66:69], v[174:177], v[142:145], v[66:69]
	s_barrier
	ds_read_b128 v[146:149], v200 offset:8192
	ds_read_b128 v[150:153], v200 offset:10240
	ds_read_b128 v[154:157], v200 offset:12288
	ds_read_b128 v[158:161], v200 offset:14336
	s_add_i32 m0, s21, 0x1c000
	s_add_u32 s40, s38, 0xb0080
	s_addc_u32 s41, s39, 0
	global_load_lds_dwordx4 v1, s[40:41]
	s_add_i32 m0, s21, 0x1e000
	s_add_u32 s40, s38, 0x108080
	s_addc_u32 s41, s39, 0
	global_load_lds_dwordx4 v1, s[40:41]
	s_waitcnt lgkmcnt(0)
	s_barrier
	v_mfma_f32_16x16x32_f16 v[62:65], v[162:165], v[146:149], v[62:65]
	v_mfma_f32_16x16x32_f16 v[58:61], v[166:169], v[146:149], v[58:61]
	v_mfma_f32_16x16x32_f16 v[54:57], v[170:173], v[146:149], v[54:57]
	v_mfma_f32_16x16x32_f16 v[50:53], v[174:177], v[146:149], v[50:53]
	v_mfma_f32_16x16x32_f16 v[46:49], v[162:165], v[150:153], v[46:49]
	v_mfma_f32_16x16x32_f16 v[42:45], v[166:169], v[150:153], v[42:45]
	v_mfma_f32_16x16x32_f16 v[38:41], v[170:173], v[150:153], v[38:41]
	v_mfma_f32_16x16x32_f16 v[34:37], v[174:177], v[150:153], v[34:37]
	v_mfma_f32_16x16x32_f16 v[30:33], v[162:165], v[154:157], v[30:33]
	v_mfma_f32_16x16x32_f16 v[26:29], v[166:169], v[154:157], v[26:29]
	v_mfma_f32_16x16x32_f16 v[22:25], v[170:173], v[154:157], v[22:25]
	v_mfma_f32_16x16x32_f16 v[18:21], v[174:177], v[154:157], v[18:21]
	v_mfma_f32_16x16x32_f16 v[14:17], v[162:165], v[158:161], v[14:17]
	v_mfma_f32_16x16x32_f16 v[10:13], v[166:169], v[158:161], v[10:13]
	v_mfma_f32_16x16x32_f16 v[6:9], v[170:173], v[158:161], v[6:9]
	v_mfma_f32_16x16x32_f16 v[2:5], v[174:177], v[158:161], v[2:5]
	s_barrier
	ds_read_b128 v[130:133], v201 offset:0
	ds_read_b128 v[134:137], v201 offset:2048
	ds_read_b128 v[138:141], v201 offset:4096
	ds_read_b128 v[142:145], v201 offset:6144
	ds_read_b128 v[162:165], v203 offset:32768
	ds_read_b128 v[166:169], v203 offset:34816
	ds_read_b128 v[170:173], v203 offset:36864
	ds_read_b128 v[174:177], v203 offset:38912
	s_add_i32 m0, s21, 0x12000
	s_add_u32 s40, s36, 0x58080
	s_addc_u32 s41, s37, 0
	global_load_lds_dwordx4 v1, s[40:41]
	s_add_i32 m0, s21, 0x16000
	s_add_u32 s40, s36, 0x108080
	s_addc_u32 s41, s37, 0
	global_load_lds_dwordx4 v1, s[40:41]
	s_waitcnt lgkmcnt(0)
	s_barrier
	v_mfma_f32_16x16x32_f16 v[126:129], v[162:165], v[130:133], v[126:129]
	v_mfma_f32_16x16x32_f16 v[122:125], v[166:169], v[130:133], v[122:125]
	v_mfma_f32_16x16x32_f16 v[118:121], v[170:173], v[130:133], v[118:121]
	v_mfma_f32_16x16x32_f16 v[114:117], v[174:177], v[130:133], v[114:117]
	v_mfma_f32_16x16x32_f16 v[110:113], v[162:165], v[134:137], v[110:113]
	v_mfma_f32_16x16x32_f16 v[106:109], v[166:169], v[134:137], v[106:109]
	v_mfma_f32_16x16x32_f16 v[102:105], v[170:173], v[134:137], v[102:105]
	v_mfma_f32_16x16x32_f16 v[98:101], v[174:177], v[134:137], v[98:101]
	v_mfma_f32_16x16x32_f16 v[94:97], v[162:165], v[138:141], v[94:97]
	v_mfma_f32_16x16x32_f16 v[90:93], v[166:169], v[138:141], v[90:93]
	v_mfma_f32_16x16x32_f16 v[86:89], v[170:173], v[138:141], v[86:89]
	v_mfma_f32_16x16x32_f16 v[82:85], v[174:177], v[138:141], v[82:85]
	v_mfma_f32_16x16x32_f16 v[78:81], v[162:165], v[142:145], v[78:81]
	v_mfma_f32_16x16x32_f16 v[74:77], v[166:169], v[142:145], v[74:77]
	v_mfma_f32_16x16x32_f16 v[70:73], v[170:173], v[142:145], v[70:73]
	v_mfma_f32_16x16x32_f16 v[66:69], v[174:177], v[142:145], v[66:69]
	s_barrier
	ds_read_b128 v[146:149], v201 offset:8192
	ds_read_b128 v[150:153], v201 offset:10240
	ds_read_b128 v[154:157], v201 offset:12288
	ds_read_b128 v[158:161], v201 offset:14336
	s_mov_b32 m0, s21
	s_add_u32 s40, s36, 0x100
	s_addc_u32 s41, s37, 0
	global_load_lds_dwordx4 v1, s[40:41]
	s_add_i32 m0, s21, 0x8000
	s_add_u32 s40, s38, 0x100
	s_addc_u32 s41, s39, 0
	global_load_lds_dwordx4 v1, s[40:41]
	s_waitcnt vmcnt(4) lgkmcnt(0)
	s_barrier
	v_mfma_f32_16x16x32_f16 v[62:65], v[162:165], v[146:149], v[62:65]
	v_mfma_f32_16x16x32_f16 v[58:61], v[166:169], v[146:149], v[58:61]
	v_mfma_f32_16x16x32_f16 v[54:57], v[170:173], v[146:149], v[54:57]
	v_mfma_f32_16x16x32_f16 v[50:53], v[174:177], v[146:149], v[50:53]
	v_mfma_f32_16x16x32_f16 v[46:49], v[162:165], v[150:153], v[46:49]
	v_mfma_f32_16x16x32_f16 v[42:45], v[166:169], v[150:153], v[42:45]
	v_mfma_f32_16x16x32_f16 v[38:41], v[170:173], v[150:153], v[38:41]
	v_mfma_f32_16x16x32_f16 v[34:37], v[174:177], v[150:153], v[34:37]
	v_mfma_f32_16x16x32_f16 v[30:33], v[162:165], v[154:157], v[30:33]
	v_mfma_f32_16x16x32_f16 v[26:29], v[166:169], v[154:157], v[26:29]
	v_mfma_f32_16x16x32_f16 v[22:25], v[170:173], v[154:157], v[22:25]
	v_mfma_f32_16x16x32_f16 v[18:21], v[174:177], v[154:157], v[18:21]
	v_mfma_f32_16x16x32_f16 v[14:17], v[162:165], v[158:161], v[14:17]
	v_mfma_f32_16x16x32_f16 v[10:13], v[166:169], v[158:161], v[10:13]
	v_mfma_f32_16x16x32_f16 v[6:9], v[170:173], v[158:161], v[6:9]
	v_mfma_f32_16x16x32_f16 v[2:5], v[174:177], v[158:161], v[2:5]
	s_barrier
	s_add_u32 s36, s36, 0x80
	s_addc_u32 s37, s37, 0
	s_add_u32 s38, s38, 0x80
	s_addc_u32 s39, s39, 0
	ds_read_b128 v[130:133], v204 offset:0
	ds_read_b128 v[134:137], v204 offset:2048
	ds_read_b128 v[138:141], v204 offset:4096
	ds_read_b128 v[142:145], v204 offset:6144
	ds_read_b128 v[162:165], v206 offset:32768
	ds_read_b128 v[166:169], v206 offset:34816
	ds_read_b128 v[170:173], v206 offset:36864
	ds_read_b128 v[174:177], v206 offset:38912
	s_add_i32 m0, s21, 0x4000
	s_add_u32 s40, s36, 0xb0080
	s_addc_u32 s41, s37, 0
	global_load_lds_dwordx4 v1, s[40:41]
	s_add_i32 m0, s21, 0xa000
	s_add_u32 s40, s38, 0x58080
	s_addc_u32 s41, s39, 0
	global_load_lds_dwordx4 v1, s[40:41]
	s_waitcnt vmcnt(4) lgkmcnt(0)
	s_barrier
	v_mfma_f32_16x16x32_f16 v[126:129], v[162:165], v[130:133], v[126:129]
	v_mfma_f32_16x16x32_f16 v[122:125], v[166:169], v[130:133], v[122:125]
	v_mfma_f32_16x16x32_f16 v[118:121], v[170:173], v[130:133], v[118:121]
	v_mfma_f32_16x16x32_f16 v[114:117], v[174:177], v[130:133], v[114:117]
	v_mfma_f32_16x16x32_f16 v[110:113], v[162:165], v[134:137], v[110:113]
	v_mfma_f32_16x16x32_f16 v[106:109], v[166:169], v[134:137], v[106:109]
	v_mfma_f32_16x16x32_f16 v[102:105], v[170:173], v[134:137], v[102:105]
	v_mfma_f32_16x16x32_f16 v[98:101], v[174:177], v[134:137], v[98:101]
	v_mfma_f32_16x16x32_f16 v[94:97], v[162:165], v[138:141], v[94:97]
	v_mfma_f32_16x16x32_f16 v[90:93], v[166:169], v[138:141], v[90:93]
	v_mfma_f32_16x16x32_f16 v[86:89], v[170:173], v[138:141], v[86:89]
	v_mfma_f32_16x16x32_f16 v[82:85], v[174:177], v[138:141], v[82:85]
	v_mfma_f32_16x16x32_f16 v[78:81], v[162:165], v[142:145], v[78:81]
	v_mfma_f32_16x16x32_f16 v[74:77], v[166:169], v[142:145], v[74:77]
	v_mfma_f32_16x16x32_f16 v[70:73], v[170:173], v[142:145], v[70:73]
	v_mfma_f32_16x16x32_f16 v[66:69], v[174:177], v[142:145], v[66:69]
	s_barrier
	ds_read_b128 v[146:149], v204 offset:8192
	ds_read_b128 v[150:153], v204 offset:10240
	ds_read_b128 v[154:157], v204 offset:12288
	ds_read_b128 v[158:161], v204 offset:14336
	s_add_i32 m0, s21, 0xc000
	s_add_u32 s40, s38, 0xb0080
	s_addc_u32 s41, s39, 0
	global_load_lds_dwordx4 v1, s[40:41]
	s_add_i32 m0, s21, 0xe000
	s_add_u32 s40, s38, 0x108080
	s_addc_u32 s41, s39, 0
	global_load_lds_dwordx4 v1, s[40:41]
	s_waitcnt lgkmcnt(0)
	s_barrier
	v_mfma_f32_16x16x32_f16 v[62:65], v[162:165], v[146:149], v[62:65]
	v_mfma_f32_16x16x32_f16 v[58:61], v[166:169], v[146:149], v[58:61]
	v_mfma_f32_16x16x32_f16 v[54:57], v[170:173], v[146:149], v[54:57]
	v_mfma_f32_16x16x32_f16 v[50:53], v[174:177], v[146:149], v[50:53]
	v_mfma_f32_16x16x32_f16 v[46:49], v[162:165], v[150:153], v[46:49]
	v_mfma_f32_16x16x32_f16 v[42:45], v[166:169], v[150:153], v[42:45]
	v_mfma_f32_16x16x32_f16 v[38:41], v[170:173], v[150:153], v[38:41]
	v_mfma_f32_16x16x32_f16 v[34:37], v[174:177], v[150:153], v[34:37]
	v_mfma_f32_16x16x32_f16 v[30:33], v[162:165], v[154:157], v[30:33]
	v_mfma_f32_16x16x32_f16 v[26:29], v[166:169], v[154:157], v[26:29]
	v_mfma_f32_16x16x32_f16 v[22:25], v[170:173], v[154:157], v[22:25]
	v_mfma_f32_16x16x32_f16 v[18:21], v[174:177], v[154:157], v[18:21]
	v_mfma_f32_16x16x32_f16 v[14:17], v[162:165], v[158:161], v[14:17]
	v_mfma_f32_16x16x32_f16 v[10:13], v[166:169], v[158:161], v[10:13]
	v_mfma_f32_16x16x32_f16 v[6:9], v[170:173], v[158:161], v[6:9]
	v_mfma_f32_16x16x32_f16 v[2:5], v[174:177], v[158:161], v[2:5]
	s_barrier
	ds_read_b128 v[130:133], v205 offset:0
	ds_read_b128 v[134:137], v205 offset:2048
	ds_read_b128 v[138:141], v205 offset:4096
	ds_read_b128 v[142:145], v205 offset:6144
	ds_read_b128 v[162:165], v207 offset:32768
	ds_read_b128 v[166:169], v207 offset:34816
	ds_read_b128 v[170:173], v207 offset:36864
	ds_read_b128 v[174:177], v207 offset:38912
	s_add_i32 m0, s21, 0x2000
	s_add_u32 s40, s36, 0x58080
	s_addc_u32 s41, s37, 0
	global_load_lds_dwordx4 v1, s[40:41]
	s_add_i32 m0, s21, 0x6000
	s_add_u32 s40, s36, 0x108080
	s_addc_u32 s41, s37, 0
	global_load_lds_dwordx4 v1, s[40:41]
	s_waitcnt lgkmcnt(0)
	s_barrier
	v_mfma_f32_16x16x32_f16 v[126:129], v[162:165], v[130:133], v[126:129]
	v_mfma_f32_16x16x32_f16 v[122:125], v[166:169], v[130:133], v[122:125]
	v_mfma_f32_16x16x32_f16 v[118:121], v[170:173], v[130:133], v[118:121]
	v_mfma_f32_16x16x32_f16 v[114:117], v[174:177], v[130:133], v[114:117]
	v_mfma_f32_16x16x32_f16 v[110:113], v[162:165], v[134:137], v[110:113]
	v_mfma_f32_16x16x32_f16 v[106:109], v[166:169], v[134:137], v[106:109]
	v_mfma_f32_16x16x32_f16 v[102:105], v[170:173], v[134:137], v[102:105]
	v_mfma_f32_16x16x32_f16 v[98:101], v[174:177], v[134:137], v[98:101]
	v_mfma_f32_16x16x32_f16 v[94:97], v[162:165], v[138:141], v[94:97]
	v_mfma_f32_16x16x32_f16 v[90:93], v[166:169], v[138:141], v[90:93]
	v_mfma_f32_16x16x32_f16 v[86:89], v[170:173], v[138:141], v[86:89]
	v_mfma_f32_16x16x32_f16 v[82:85], v[174:177], v[138:141], v[82:85]
	v_mfma_f32_16x16x32_f16 v[78:81], v[162:165], v[142:145], v[78:81]
	v_mfma_f32_16x16x32_f16 v[74:77], v[166:169], v[142:145], v[74:77]
	v_mfma_f32_16x16x32_f16 v[70:73], v[170:173], v[142:145], v[70:73]
	v_mfma_f32_16x16x32_f16 v[66:69], v[174:177], v[142:145], v[66:69]
	s_barrier
	ds_read_b128 v[146:149], v205 offset:8192
	ds_read_b128 v[150:153], v205 offset:10240
	ds_read_b128 v[154:157], v205 offset:12288
	ds_read_b128 v[158:161], v205 offset:14336
	s_add_i32 m0, s21, 0x10000
	s_add_u32 s40, s36, 0x100
	s_addc_u32 s41, s37, 0
	global_load_lds_dwordx4 v1, s[40:41]
	s_add_i32 m0, s21, 0x18000
	s_add_u32 s40, s38, 0x100
	s_addc_u32 s41, s39, 0
	global_load_lds_dwordx4 v1, s[40:41]
	s_waitcnt vmcnt(4) lgkmcnt(0)
	s_barrier
	v_mfma_f32_16x16x32_f16 v[62:65], v[162:165], v[146:149], v[62:65]
	v_mfma_f32_16x16x32_f16 v[58:61], v[166:169], v[146:149], v[58:61]
	v_mfma_f32_16x16x32_f16 v[54:57], v[170:173], v[146:149], v[54:57]
	v_mfma_f32_16x16x32_f16 v[50:53], v[174:177], v[146:149], v[50:53]
	v_mfma_f32_16x16x32_f16 v[46:49], v[162:165], v[150:153], v[46:49]
	v_mfma_f32_16x16x32_f16 v[42:45], v[166:169], v[150:153], v[42:45]
	v_mfma_f32_16x16x32_f16 v[38:41], v[170:173], v[150:153], v[38:41]
	v_mfma_f32_16x16x32_f16 v[34:37], v[174:177], v[150:153], v[34:37]
	v_mfma_f32_16x16x32_f16 v[30:33], v[162:165], v[154:157], v[30:33]
	v_mfma_f32_16x16x32_f16 v[26:29], v[166:169], v[154:157], v[26:29]
	v_mfma_f32_16x16x32_f16 v[22:25], v[170:173], v[154:157], v[22:25]
	v_mfma_f32_16x16x32_f16 v[18:21], v[174:177], v[154:157], v[18:21]
	v_mfma_f32_16x16x32_f16 v[14:17], v[162:165], v[158:161], v[14:17]
	v_mfma_f32_16x16x32_f16 v[10:13], v[166:169], v[158:161], v[10:13]
	v_mfma_f32_16x16x32_f16 v[6:9], v[170:173], v[158:161], v[6:9]
	v_mfma_f32_16x16x32_f16 v[2:5], v[174:177], v[158:161], v[2:5]
	s_barrier
	s_add_u32 s36, s36, 0x80
	s_addc_u32 s37, s37, 0
	s_add_u32 s38, s38, 0x80
	s_addc_u32 s39, s39, 0
	s_add_i32 s23, s23, -1
	s_cmp_lg_u32 s23, 0
	s_cbranch_scc1 .Lp5_loop
	ds_read_b128 v[130:133], v200 offset:0
	ds_read_b128 v[134:137], v200 offset:2048
	ds_read_b128 v[138:141], v200 offset:4096
	ds_read_b128 v[142:145], v200 offset:6144
	ds_read_b128 v[162:165], v202 offset:32768
	ds_read_b128 v[166:169], v202 offset:34816
	ds_read_b128 v[170:173], v202 offset:36864
	ds_read_b128 v[174:177], v202 offset:38912
	s_add_i32 m0, s21, 0x14000
	s_add_u32 s40, s36, 0xb0080
	s_addc_u32 s41, s37, 0
	global_load_lds_dwordx4 v1, s[40:41]
	s_add_i32 m0, s21, 0x1a000
	s_add_u32 s40, s38, 0x58080
	s_addc_u32 s41, s39, 0
	global_load_lds_dwordx4 v1, s[40:41]
	s_waitcnt vmcnt(4) lgkmcnt(0)
	s_barrier
	v_mfma_f32_16x16x32_f16 v[126:129], v[162:165], v[130:133], v[126:129]
	v_mfma_f32_16x16x32_f16 v[122:125], v[166:169], v[130:133], v[122:125]
	v_mfma_f32_16x16x32_f16 v[118:121], v[170:173], v[130:133], v[118:121]
	v_mfma_f32_16x16x32_f16 v[114:117], v[174:177], v[130:133], v[114:117]
	v_mfma_f32_16x16x32_f16 v[110:113], v[162:165], v[134:137], v[110:113]
	v_mfma_f32_16x16x32_f16 v[106:109], v[166:169], v[134:137], v[106:109]
	v_mfma_f32_16x16x32_f16 v[102:105], v[170:173], v[134:137], v[102:105]
	v_mfma_f32_16x16x32_f16 v[98:101], v[174:177], v[134:137], v[98:101]
	v_mfma_f32_16x16x32_f16 v[94:97], v[162:165], v[138:141], v[94:97]
	v_mfma_f32_16x16x32_f16 v[90:93], v[166:169], v[138:141], v[90:93]
	v_mfma_f32_16x16x32_f16 v[86:89], v[170:173], v[138:141], v[86:89]
	v_mfma_f32_16x16x32_f16 v[82:85], v[174:177], v[138:141], v[82:85]
	v_mfma_f32_16x16x32_f16 v[78:81], v[162:165], v[142:145], v[78:81]
	v_mfma_f32_16x16x32_f16 v[74:77], v[166:169], v[142:145], v[74:77]
	v_mfma_f32_16x16x32_f16 v[70:73], v[170:173], v[142:145], v[70:73]
	v_mfma_f32_16x16x32_f16 v[66:69], v[174:177], v[142:145], v[66:69]
	s_barrier
	ds_read_b128 v[146:149], v200 offset:8192
	ds_read_b128 v[150:153], v200 offset:10240
	ds_read_b128 v[154:157], v200 offset:12288
	ds_read_b128 v[158:161], v200 offset:14336
	s_add_i32 m0, s21, 0x1c000
	s_add_u32 s40, s38, 0xb0080
	s_addc_u32 s41, s39, 0
	global_load_lds_dwordx4 v1, s[40:41]
	s_add_i32 m0, s21, 0x1e000
	s_add_u32 s40, s38, 0x108080
	s_addc_u32 s41, s39, 0
	global_load_lds_dwordx4 v1, s[40:41]
	s_waitcnt lgkmcnt(0)
	s_barrier
	v_mfma_f32_16x16x32_f16 v[62:65], v[162:165], v[146:149], v[62:65]
	v_mfma_f32_16x16x32_f16 v[58:61], v[166:169], v[146:149], v[58:61]
	v_mfma_f32_16x16x32_f16 v[54:57], v[170:173], v[146:149], v[54:57]
	v_mfma_f32_16x16x32_f16 v[50:53], v[174:177], v[146:149], v[50:53]
	v_mfma_f32_16x16x32_f16 v[46:49], v[162:165], v[150:153], v[46:49]
	v_mfma_f32_16x16x32_f16 v[42:45], v[166:169], v[150:153], v[42:45]
	v_mfma_f32_16x16x32_f16 v[38:41], v[170:173], v[150:153], v[38:41]
	v_mfma_f32_16x16x32_f16 v[34:37], v[174:177], v[150:153], v[34:37]
	v_mfma_f32_16x16x32_f16 v[30:33], v[162:165], v[154:157], v[30:33]
	v_mfma_f32_16x16x32_f16 v[26:29], v[166:169], v[154:157], v[26:29]
	v_mfma_f32_16x16x32_f16 v[22:25], v[170:173], v[154:157], v[22:25]
	v_mfma_f32_16x16x32_f16 v[18:21], v[174:177], v[154:157], v[18:21]
	v_mfma_f32_16x16x32_f16 v[14:17], v[162:165], v[158:161], v[14:17]
	v_mfma_f32_16x16x32_f16 v[10:13], v[166:169], v[158:161], v[10:13]
	v_mfma_f32_16x16x32_f16 v[6:9], v[170:173], v[158:161], v[6:9]
	v_mfma_f32_16x16x32_f16 v[2:5], v[174:177], v[158:161], v[2:5]
	s_barrier
	ds_read_b128 v[130:133], v201 offset:0
	ds_read_b128 v[134:137], v201 offset:2048
	ds_read_b128 v[138:141], v201 offset:4096
	ds_read_b128 v[142:145], v201 offset:6144
	ds_read_b128 v[162:165], v203 offset:32768
	ds_read_b128 v[166:169], v203 offset:34816
	ds_read_b128 v[170:173], v203 offset:36864
	ds_read_b128 v[174:177], v203 offset:38912
	s_add_i32 m0, s21, 0x12000
	s_add_u32 s40, s36, 0x58080
	s_addc_u32 s41, s37, 0
	global_load_lds_dwordx4 v1, s[40:41]
	s_add_i32 m0, s21, 0x16000
	s_add_u32 s40, s36, 0x108080
	s_addc_u32 s41, s37, 0
	global_load_lds_dwordx4 v1, s[40:41]
	s_waitcnt lgkmcnt(0)
	s_barrier
	v_mfma_f32_16x16x32_f16 v[126:129], v[162:165], v[130:133], v[126:129]
	v_mfma_f32_16x16x32_f16 v[122:125], v[166:169], v[130:133], v[122:125]
	v_mfma_f32_16x16x32_f16 v[118:121], v[170:173], v[130:133], v[118:121]
	v_mfma_f32_16x16x32_f16 v[114:117], v[174:177], v[130:133], v[114:117]
	v_mfma_f32_16x16x32_f16 v[110:113], v[162:165], v[134:137], v[110:113]
	v_mfma_f32_16x16x32_f16 v[106:109], v[166:169], v[134:137], v[106:109]
	v_mfma_f32_16x16x32_f16 v[102:105], v[170:173], v[134:137], v[102:105]
	v_mfma_f32_16x16x32_f16 v[98:101], v[174:177], v[134:137], v[98:101]
	v_mfma_f32_16x16x32_f16 v[94:97], v[162:165], v[138:141], v[94:97]
	v_mfma_f32_16x16x32_f16 v[90:93], v[166:169], v[138:141], v[90:93]
	v_mfma_f32_16x16x32_f16 v[86:89], v[170:173], v[138:141], v[86:89]
	v_mfma_f32_16x16x32_f16 v[82:85], v[174:177], v[138:141], v[82:85]
	v_mfma_f32_16x16x32_f16 v[78:81], v[162:165], v[142:145], v[78:81]
	v_mfma_f32_16x16x32_f16 v[74:77], v[166:169], v[142:145], v[74:77]
	v_mfma_f32_16x16x32_f16 v[70:73], v[170:173], v[142:145], v[70:73]
	v_mfma_f32_16x16x32_f16 v[66:69], v[174:177], v[142:145], v[66:69]
	s_barrier
	ds_read_b128 v[146:149], v201 offset:8192
	ds_read_b128 v[150:153], v201 offset:10240
	ds_read_b128 v[154:157], v201 offset:12288
	ds_read_b128 v[158:161], v201 offset:14336
	s_waitcnt vmcnt(2) lgkmcnt(0)
	s_barrier
	v_mfma_f32_16x16x32_f16 v[62:65], v[162:165], v[146:149], v[62:65]
	v_mfma_f32_16x16x32_f16 v[58:61], v[166:169], v[146:149], v[58:61]
	v_mfma_f32_16x16x32_f16 v[54:57], v[170:173], v[146:149], v[54:57]
	v_mfma_f32_16x16x32_f16 v[50:53], v[174:177], v[146:149], v[50:53]
	v_mfma_f32_16x16x32_f16 v[46:49], v[162:165], v[150:153], v[46:49]
	v_mfma_f32_16x16x32_f16 v[42:45], v[166:169], v[150:153], v[42:45]
	v_mfma_f32_16x16x32_f16 v[38:41], v[170:173], v[150:153], v[38:41]
	v_mfma_f32_16x16x32_f16 v[34:37], v[174:177], v[150:153], v[34:37]
	v_mfma_f32_16x16x32_f16 v[30:33], v[162:165], v[154:157], v[30:33]
	v_mfma_f32_16x16x32_f16 v[26:29], v[166:169], v[154:157], v[26:29]
	v_mfma_f32_16x16x32_f16 v[22:25], v[170:173], v[154:157], v[22:25]
	v_mfma_f32_16x16x32_f16 v[18:21], v[174:177], v[154:157], v[18:21]
	v_mfma_f32_16x16x32_f16 v[14:17], v[162:165], v[158:161], v[14:17]
	v_mfma_f32_16x16x32_f16 v[10:13], v[166:169], v[158:161], v[10:13]
	v_mfma_f32_16x16x32_f16 v[6:9], v[170:173], v[158:161], v[6:9]
	v_mfma_f32_16x16x32_f16 v[2:5], v[174:177], v[158:161], v[2:5]
	s_barrier
	s_add_u32 s36, s36, 0x80
	s_addc_u32 s37, s37, 0
	s_add_u32 s38, s38, 0x80
	s_addc_u32 s39, s39, 0
	ds_read_b128 v[130:133], v204 offset:0
	ds_read_b128 v[134:137], v204 offset:2048
	ds_read_b128 v[138:141], v204 offset:4096
	ds_read_b128 v[142:145], v204 offset:6144
	ds_read_b128 v[162:165], v206 offset:32768
	ds_read_b128 v[166:169], v206 offset:34816
	ds_read_b128 v[170:173], v206 offset:36864
	ds_read_b128 v[174:177], v206 offset:38912
	s_waitcnt vmcnt(0) lgkmcnt(0)
	s_barrier
	v_mfma_f32_16x16x32_f16 v[126:129], v[162:165], v[130:133], v[126:129]
	v_mfma_f32_16x16x32_f16 v[122:125], v[166:169], v[130:133], v[122:125]
	v_mfma_f32_16x16x32_f16 v[118:121], v[170:173], v[130:133], v[118:121]
	v_mfma_f32_16x16x32_f16 v[114:117], v[174:177], v[130:133], v[114:117]
	v_mfma_f32_16x16x32_f16 v[110:113], v[162:165], v[134:137], v[110:113]
	v_mfma_f32_16x16x32_f16 v[106:109], v[166:169], v[134:137], v[106:109]
	v_mfma_f32_16x16x32_f16 v[102:105], v[170:173], v[134:137], v[102:105]
	v_mfma_f32_16x16x32_f16 v[98:101], v[174:177], v[134:137], v[98:101]
	v_mfma_f32_16x16x32_f16 v[94:97], v[162:165], v[138:141], v[94:97]
	v_mfma_f32_16x16x32_f16 v[90:93], v[166:169], v[138:141], v[90:93]
	v_mfma_f32_16x16x32_f16 v[86:89], v[170:173], v[138:141], v[86:89]
	v_mfma_f32_16x16x32_f16 v[82:85], v[174:177], v[138:141], v[82:85]
	v_mfma_f32_16x16x32_f16 v[78:81], v[162:165], v[142:145], v[78:81]
	v_mfma_f32_16x16x32_f16 v[74:77], v[166:169], v[142:145], v[74:77]
	v_mfma_f32_16x16x32_f16 v[70:73], v[170:173], v[142:145], v[70:73]
	v_mfma_f32_16x16x32_f16 v[66:69], v[174:177], v[142:145], v[66:69]
	s_barrier
	ds_read_b128 v[146:149], v204 offset:8192
	ds_read_b128 v[150:153], v204 offset:10240
	ds_read_b128 v[154:157], v204 offset:12288
	ds_read_b128 v[158:161], v204 offset:14336
	s_waitcnt lgkmcnt(0)
	s_barrier
	v_mfma_f32_16x16x32_f16 v[62:65], v[162:165], v[146:149], v[62:65]
	v_mfma_f32_16x16x32_f16 v[58:61], v[166:169], v[146:149], v[58:61]
	v_mfma_f32_16x16x32_f16 v[54:57], v[170:173], v[146:149], v[54:57]
	v_mfma_f32_16x16x32_f16 v[50:53], v[174:177], v[146:149], v[50:53]
	v_mfma_f32_16x16x32_f16 v[46:49], v[162:165], v[150:153], v[46:49]
	v_mfma_f32_16x16x32_f16 v[42:45], v[166:169], v[150:153], v[42:45]
	v_mfma_f32_16x16x32_f16 v[38:41], v[170:173], v[150:153], v[38:41]
	v_mfma_f32_16x16x32_f16 v[34:37], v[174:177], v[150:153], v[34:37]
	v_mfma_f32_16x16x32_f16 v[30:33], v[162:165], v[154:157], v[30:33]
	v_mfma_f32_16x16x32_f16 v[26:29], v[166:169], v[154:157], v[26:29]
	v_mfma_f32_16x16x32_f16 v[22:25], v[170:173], v[154:157], v[22:25]
	v_mfma_f32_16x16x32_f16 v[18:21], v[174:177], v[154:157], v[18:21]
	v_mfma_f32_16x16x32_f16 v[14:17], v[162:165], v[158:161], v[14:17]
	v_mfma_f32_16x16x32_f16 v[10:13], v[166:169], v[158:161], v[10:13]
	v_mfma_f32_16x16x32_f16 v[6:9], v[170:173], v[158:161], v[6:9]
	v_mfma_f32_16x16x32_f16 v[2:5], v[174:177], v[158:161], v[2:5]
	s_barrier
	ds_read_b128 v[130:133], v205 offset:0
	ds_read_b128 v[134:137], v205 offset:2048
	ds_read_b128 v[138:141], v205 offset:4096
	ds_read_b128 v[142:145], v205 offset:6144
	ds_read_b128 v[162:165], v207 offset:32768
	ds_read_b128 v[166:169], v207 offset:34816
	ds_read_b128 v[170:173], v207 offset:36864
	ds_read_b128 v[174:177], v207 offset:38912
	s_waitcnt lgkmcnt(0)
	s_barrier
	v_mfma_f32_16x16x32_f16 v[126:129], v[162:165], v[130:133], v[126:129]
	v_mfma_f32_16x16x32_f16 v[122:125], v[166:169], v[130:133], v[122:125]
	v_mfma_f32_16x16x32_f16 v[118:121], v[170:173], v[130:133], v[118:121]
	v_mfma_f32_16x16x32_f16 v[114:117], v[174:177], v[130:133], v[114:117]
	v_mfma_f32_16x16x32_f16 v[110:113], v[162:165], v[134:137], v[110:113]
	v_mfma_f32_16x16x32_f16 v[106:109], v[166:169], v[134:137], v[106:109]
	v_mfma_f32_16x16x32_f16 v[102:105], v[170:173], v[134:137], v[102:105]
	v_mfma_f32_16x16x32_f16 v[98:101], v[174:177], v[134:137], v[98:101]
	v_mfma_f32_16x16x32_f16 v[94:97], v[162:165], v[138:141], v[94:97]
	v_mfma_f32_16x16x32_f16 v[90:93], v[166:169], v[138:141], v[90:93]
	v_mfma_f32_16x16x32_f16 v[86:89], v[170:173], v[138:141], v[86:89]
	v_mfma_f32_16x16x32_f16 v[82:85], v[174:177], v[138:141], v[82:85]
	v_mfma_f32_16x16x32_f16 v[78:81], v[162:165], v[142:145], v[78:81]
	v_mfma_f32_16x16x32_f16 v[74:77], v[166:169], v[142:145], v[74:77]
	v_mfma_f32_16x16x32_f16 v[70:73], v[170:173], v[142:145], v[70:73]
	v_mfma_f32_16x16x32_f16 v[66:69], v[174:177], v[142:145], v[66:69]
	s_barrier
	ds_read_b128 v[146:149], v205 offset:8192
	ds_read_b128 v[150:153], v205 offset:10240
	ds_read_b128 v[154:157], v205 offset:12288
	ds_read_b128 v[158:161], v205 offset:14336
	s_waitcnt lgkmcnt(0)
	s_barrier
	v_mfma_f32_16x16x32_f16 v[62:65], v[162:165], v[146:149], v[62:65]
	v_mfma_f32_16x16x32_f16 v[58:61], v[166:169], v[146:149], v[58:61]
	v_mfma_f32_16x16x32_f16 v[54:57], v[170:173], v[146:149], v[54:57]
	v_mfma_f32_16x16x32_f16 v[50:53], v[174:177], v[146:149], v[50:53]
	v_mfma_f32_16x16x32_f16 v[46:49], v[162:165], v[150:153], v[46:49]
	v_mfma_f32_16x16x32_f16 v[42:45], v[166:169], v[150:153], v[42:45]
	v_mfma_f32_16x16x32_f16 v[38:41], v[170:173], v[150:153], v[38:41]
	v_mfma_f32_16x16x32_f16 v[34:37], v[174:177], v[150:153], v[34:37]
	v_mfma_f32_16x16x32_f16 v[30:33], v[162:165], v[154:157], v[30:33]
	v_mfma_f32_16x16x32_f16 v[26:29], v[166:169], v[154:157], v[26:29]
	v_mfma_f32_16x16x32_f16 v[22:25], v[170:173], v[154:157], v[22:25]
	v_mfma_f32_16x16x32_f16 v[18:21], v[174:177], v[154:157], v[18:21]
	v_mfma_f32_16x16x32_f16 v[14:17], v[162:165], v[158:161], v[14:17]
	v_mfma_f32_16x16x32_f16 v[10:13], v[166:169], v[158:161], v[10:13]
	v_mfma_f32_16x16x32_f16 v[6:9], v[170:173], v[158:161], v[6:9]
	v_mfma_f32_16x16x32_f16 v[2:5], v[174:177], v[158:161], v[2:5]
	s_barrier
	s_cmp_eq_u32 s22, 1
	s_cbranch_scc1 .Lp5_skew1
	s_barrier
.Lp5_skew1:
	s_nop 7
	s_nop 1
	s_cmp_lt_u32 s20, 0x80
	v_readlane_b32 s4, v254, 55
	v_readlane_b32 s5, v254, 56
	v_readlane_b32 s2, v254, 12
	v_readlane_b32 s3, v254, 13
	s_cselect_b32 s42, s2, s4
	s_cselect_b32 s43, s3, s5
	s_and_b32 s2, s20, 0x7f
	s_lshl_b32 s2, s2, 20
	s_lshl_b32 s3, s19, 10
	s_add_i32 s2, s2, s3
	s_add_u32 s42, s42, s2
	s_addc_u32 s43, s43, 0
	s_lshr_b32 s2, s20, 3
	s_cmp_lt_u32 s20, 0x80
	s_cselect_b32 s2, s2, 16
	s_add_i32 s2, s2, s54
	s_mul_i32 s2, s2, 0x6000
	s_add_i32 s2, s2, s3
	s_add_i32 s2, s2, 0x5000
	v_readlane_b32 s4, v254, 14
	v_readlane_b32 s5, v254, 15
	s_nop 3
	s_add_u32 s44, s4, s2
	s_addc_u32 s45, s5, 0
	v_and_b32_e32 v197, 15, v222
	v_lshrrev_b32_e32 v198, 8, v222
	v_lshl_or_b32 v197, v198, 7, v197
	v_bfe_u32 v198, v222, 6, 2
	v_bfe_u32 v199, v222, 4, 2
	v_lshlrev_b32_e32 v199, 4, v199
	v_lshl_or_b32 v196, v198, 8, v199
	v_lshl_or_b32 v194, v197, 12, v196
	v_mov_b32_e32 v195, v194
	global_load_dwordx4 v[178:181], v196, s[44:45] offset:0
	global_load_dwordx4 v[182:185], v196, s[44:45] offset:64
	global_load_dwordx4 v[186:189], v196, s[44:45] offset:128
	global_load_dwordx4 v[190:193], v196, s[44:45] offset:192
	global_load_dwordx4 v[130:133], v194, s[42:43] offset:0
	global_load_dwordx4 v[134:137], v194, s[42:43] offset:64
	global_load_dwordx4 v[138:141], v194, s[42:43] offset:128
	global_load_dwordx4 v[142:145], v194, s[42:43] offset:192
	v_add_u32_e32 v194, 0x10000, v194
	global_load_dwordx4 v[146:149], v194, s[42:43] offset:0
	global_load_dwordx4 v[150:153], v194, s[42:43] offset:64
	global_load_dwordx4 v[154:157], v194, s[42:43] offset:128
	global_load_dwordx4 v[158:161], v194, s[42:43] offset:192
	v_add_u32_e32 v194, 0x10000, v194
	global_load_dwordx4 v[162:165], v194, s[42:43] offset:0
	global_load_dwordx4 v[166:169], v194, s[42:43] offset:64
	global_load_dwordx4 v[170:173], v194, s[42:43] offset:128
	global_load_dwordx4 v[174:177], v194, s[42:43] offset:192
	v_add_u32_e32 v194, 0x10000, v194
	s_add_i32 s2, s18, s95
	s_cmp_lt_i32 s2, s53
	s_cselect_b32 s28, 1, 0
	s_cselect_b32 s18, s2, s18
	s_lshr_b32 s2, s18, 5
	s_lshl_b32 s2, s2, 3
	s_and_b32 s3, s18, 7
	s_add_i32 s20, s2, s3
	s_bfe_u32 s19, s18, 0x20003
	s_mul_i32 s2, s20, 0x160000
	s_add_u32 s36, s96, s2
	s_addc_u32 s37, s97, 0
	s_mul_i32 s2, s19, 0x160000
	s_add_u32 s38, s16, s2
	s_addc_u32 s39, s17, 0
	s_mov_b32 m0, s21
	s_nop 0
	global_load_lds_dwordx4 v1, s[36:37]
	s_add_i32 m0, s21, 0x2000
	s_add_u32 s40, s36, 0x58000
	s_addc_u32 s41, s37, 0
	global_load_lds_dwordx4 v1, s[40:41]
	s_add_i32 m0, s21, 0x4000
	s_add_u32 s40, s36, 0xb0000
	s_addc_u32 s41, s37, 0
	global_load_lds_dwordx4 v1, s[40:41]
	s_add_i32 m0, s21, 0x6000
	s_add_u32 s40, s36, 0x108000
	s_addc_u32 s41, s37, 0
	global_load_lds_dwordx4 v1, s[40:41]
	s_add_i32 m0, s21, 0x8000
	s_nop 0
	global_load_lds_dwordx4 v1, s[38:39]
	s_add_i32 m0, s21, 0xa000
	s_add_u32 s40, s38, 0x58000
	s_addc_u32 s41, s39, 0
	global_load_lds_dwordx4 v1, s[40:41]
	s_add_i32 m0, s21, 0xc000
	s_add_u32 s40, s38, 0xb0000
	s_addc_u32 s41, s39, 0
	global_load_lds_dwordx4 v1, s[40:41]
	s_add_i32 m0, s21, 0xe000
	s_add_u32 s40, s38, 0x108000
	s_addc_u32 s41, s39, 0
	global_load_lds_dwordx4 v1, s[40:41]
	s_waitcnt vmcnt(16)
	v_pk_fma_f32 v[126:127], v[126:127], v[178:179], v[130:131]
	v_pk_fma_f32 v[128:129], v[128:129], v[180:181], v[132:133]
	v_pk_fma_f32 v[122:123], v[122:123], v[182:183], v[134:135]
	v_pk_fma_f32 v[124:125], v[124:125], v[184:185], v[136:137]
	v_pk_fma_f32 v[118:119], v[118:119], v[186:187], v[138:139]
	v_pk_fma_f32 v[120:121], v[120:121], v[188:189], v[140:141]
	v_pk_fma_f32 v[114:115], v[114:115], v[190:191], v[142:143]
	v_pk_fma_f32 v[116:117], v[116:117], v[192:193], v[144:145]
	global_store_dwordx4 v195, v[126:129], s[42:43] offset:0
	global_store_dwordx4 v195, v[122:125], s[42:43] offset:64
	global_store_dwordx4 v195, v[118:121], s[42:43] offset:128
	global_store_dwordx4 v195, v[114:117], s[42:43] offset:192
	global_load_dwordx4 v[130:133], v194, s[42:43] offset:0
	global_load_dwordx4 v[134:137], v194, s[42:43] offset:64
	global_load_dwordx4 v[138:141], v194, s[42:43] offset:128
	global_load_dwordx4 v[142:145], v194, s[42:43] offset:192
	v_add_u32_e32 v194, 0x10000, v194
	s_waitcnt vmcnt(20)
	v_add_u32_e32 v195, 0x10000, v195
	v_pk_fma_f32 v[110:111], v[110:111], v[178:179], v[146:147]
	v_pk_fma_f32 v[112:113], v[112:113], v[180:181], v[148:149]
	v_pk_fma_f32 v[106:107], v[106:107], v[182:183], v[150:151]
	v_pk_fma_f32 v[108:109], v[108:109], v[184:185], v[152:153]
	v_pk_fma_f32 v[102:103], v[102:103], v[186:187], v[154:155]
	v_pk_fma_f32 v[104:105], v[104:105], v[188:189], v[156:157]
	v_pk_fma_f32 v[98:99], v[98:99], v[190:191], v[158:159]
	v_pk_fma_f32 v[100:101], v[100:101], v[192:193], v[160:161]
	global_store_dwordx4 v195, v[110:113], s[42:43] offset:0
	global_store_dwordx4 v195, v[106:109], s[42:43] offset:64
	global_store_dwordx4 v195, v[102:105], s[42:43] offset:128
	global_store_dwordx4 v195, v[98:101], s[42:43] offset:192
	global_load_dwordx4 v[146:149], v194, s[42:43] offset:0
	global_load_dwordx4 v[150:153], v194, s[42:43] offset:64
	global_load_dwordx4 v[154:157], v194, s[42:43] offset:128
	global_load_dwordx4 v[158:161], v194, s[42:43] offset:192
	v_add_u32_e32 v194, 0x10000, v194
	s_waitcnt vmcnt(24)
	v_add_u32_e32 v195, 0x10000, v195
	v_pk_fma_f32 v[94:95], v[94:95], v[178:179], v[162:163]
	v_pk_fma_f32 v[96:97], v[96:97], v[180:181], v[164:165]
	v_pk_fma_f32 v[90:91], v[90:91], v[182:183], v[166:167]
	v_pk_fma_f32 v[92:93], v[92:93], v[184:185], v[168:169]
	v_pk_fma_f32 v[86:87], v[86:87], v[186:187], v[170:171]
	v_pk_fma_f32 v[88:89], v[88:89], v[188:189], v[172:173]
	v_pk_fma_f32 v[82:83], v[82:83], v[190:191], v[174:175]
	v_pk_fma_f32 v[84:85], v[84:85], v[192:193], v[176:177]
	global_store_dwordx4 v195, v[94:97], s[42:43] offset:0
	global_store_dwordx4 v195, v[90:93], s[42:43] offset:64
	global_store_dwordx4 v195, v[86:89], s[42:43] offset:128
	global_store_dwordx4 v195, v[82:85], s[42:43] offset:192
	global_load_dwordx4 v[162:165], v194, s[42:43] offset:0
	global_load_dwordx4 v[166:169], v194, s[42:43] offset:64
	global_load_dwordx4 v[170:173], v194, s[42:43] offset:128
	global_load_dwordx4 v[174:177], v194, s[42:43] offset:192
	v_add_u32_e32 v194, 0x10000, v194
	s_waitcnt vmcnt(16)
	v_add_u32_e32 v195, 0x10000, v195
	v_pk_fma_f32 v[78:79], v[78:79], v[178:179], v[130:131]
	v_pk_fma_f32 v[80:81], v[80:81], v[180:181], v[132:133]
	v_pk_fma_f32 v[74:75], v[74:75], v[182:183], v[134:135]
	v_pk_fma_f32 v[76:77], v[76:77], v[184:185], v[136:137]
	v_pk_fma_f32 v[70:71], v[70:71], v[186:187], v[138:139]
	v_pk_fma_f32 v[72:73], v[72:73], v[188:189], v[140:141]
	v_pk_fma_f32 v[66:67], v[66:67], v[190:191], v[142:143]
	v_pk_fma_f32 v[68:69], v[68:69], v[192:193], v[144:145]
	global_store_dwordx4 v195, v[78:81], s[42:43] offset:0
	global_store_dwordx4 v195, v[74:77], s[42:43] offset:64
	global_store_dwordx4 v195, v[70:73], s[42:43] offset:128
	global_store_dwordx4 v195, v[66:69], s[42:43] offset:192
	global_load_dwordx4 v[130:133], v194, s[42:43] offset:0
	global_load_dwordx4 v[134:137], v194, s[42:43] offset:64
	global_load_dwordx4 v[138:141], v194, s[42:43] offset:128
	global_load_dwordx4 v[142:145], v194, s[42:43] offset:192
	v_add_u32_e32 v194, 0x10000, v194
	s_waitcnt vmcnt(16)
	v_add_u32_e32 v195, 0x10000, v195
	v_pk_fma_f32 v[62:63], v[62:63], v[178:179], v[146:147]
	v_pk_fma_f32 v[64:65], v[64:65], v[180:181], v[148:149]
	v_pk_fma_f32 v[58:59], v[58:59], v[182:183], v[150:151]
	v_pk_fma_f32 v[60:61], v[60:61], v[184:185], v[152:153]
	v_pk_fma_f32 v[54:55], v[54:55], v[186:187], v[154:155]
	v_pk_fma_f32 v[56:57], v[56:57], v[188:189], v[156:157]
	v_pk_fma_f32 v[50:51], v[50:51], v[190:191], v[158:159]
	v_pk_fma_f32 v[52:53], v[52:53], v[192:193], v[160:161]
	global_store_dwordx4 v195, v[62:65], s[42:43] offset:0
	global_store_dwordx4 v195, v[58:61], s[42:43] offset:64
	global_store_dwordx4 v195, v[54:57], s[42:43] offset:128
	global_store_dwordx4 v195, v[50:53], s[42:43] offset:192
	global_load_dwordx4 v[146:149], v194, s[42:43] offset:0
	global_load_dwordx4 v[150:153], v194, s[42:43] offset:64
	global_load_dwordx4 v[154:157], v194, s[42:43] offset:128
	global_load_dwordx4 v[158:161], v194, s[42:43] offset:192
	v_add_u32_e32 v194, 0x10000, v194
	s_waitcnt vmcnt(16)
	v_add_u32_e32 v195, 0x10000, v195
	v_pk_fma_f32 v[46:47], v[46:47], v[178:179], v[162:163]
	v_pk_fma_f32 v[48:49], v[48:49], v[180:181], v[164:165]
	v_pk_fma_f32 v[42:43], v[42:43], v[182:183], v[166:167]
	v_pk_fma_f32 v[44:45], v[44:45], v[184:185], v[168:169]
	v_pk_fma_f32 v[38:39], v[38:39], v[186:187], v[170:171]
	v_pk_fma_f32 v[40:41], v[40:41], v[188:189], v[172:173]
	v_pk_fma_f32 v[34:35], v[34:35], v[190:191], v[174:175]
	v_pk_fma_f32 v[36:37], v[36:37], v[192:193], v[176:177]
	global_store_dwordx4 v195, v[46:49], s[42:43] offset:0
	global_store_dwordx4 v195, v[42:45], s[42:43] offset:64
	global_store_dwordx4 v195, v[38:41], s[42:43] offset:128
	global_store_dwordx4 v195, v[34:37], s[42:43] offset:192
	s_waitcnt vmcnt(12)
	v_add_u32_e32 v195, 0x10000, v195
	v_pk_fma_f32 v[30:31], v[30:31], v[178:179], v[130:131]
	v_pk_fma_f32 v[32:33], v[32:33], v[180:181], v[132:133]
	v_pk_fma_f32 v[26:27], v[26:27], v[182:183], v[134:135]
	v_pk_fma_f32 v[28:29], v[28:29], v[184:185], v[136:137]
	v_pk_fma_f32 v[22:23], v[22:23], v[186:187], v[138:139]
	v_pk_fma_f32 v[24:25], v[24:25], v[188:189], v[140:141]
	v_pk_fma_f32 v[18:19], v[18:19], v[190:191], v[142:143]
	v_pk_fma_f32 v[20:21], v[20:21], v[192:193], v[144:145]
	global_store_dwordx4 v195, v[30:33], s[42:43] offset:0
	global_store_dwordx4 v195, v[26:29], s[42:43] offset:64
	global_store_dwordx4 v195, v[22:25], s[42:43] offset:128
	global_store_dwordx4 v195, v[18:21], s[42:43] offset:192
	s_waitcnt vmcnt(8)
	v_add_u32_e32 v195, 0x10000, v195
	v_pk_fma_f32 v[14:15], v[14:15], v[178:179], v[146:147]
	v_pk_fma_f32 v[16:17], v[16:17], v[180:181], v[148:149]
	v_pk_fma_f32 v[10:11], v[10:11], v[182:183], v[150:151]
	v_pk_fma_f32 v[12:13], v[12:13], v[184:185], v[152:153]
	v_pk_fma_f32 v[6:7], v[6:7], v[186:187], v[154:155]
	v_pk_fma_f32 v[8:9], v[8:9], v[188:189], v[156:157]
	v_pk_fma_f32 v[2:3], v[2:3], v[190:191], v[158:159]
	v_pk_fma_f32 v[4:5], v[4:5], v[192:193], v[160:161]
	global_store_dwordx4 v195, v[14:17], s[42:43] offset:0
	global_store_dwordx4 v195, v[10:13], s[42:43] offset:64
	global_store_dwordx4 v195, v[6:9], s[42:43] offset:128
	global_store_dwordx4 v195, v[2:5], s[42:43] offset:192
	s_cmp_lg_u32 s28, 0
	s_cbranch_scc1 .Lp5_cont
	v_readlane_b32 s36, v254, 0
	v_readlane_b32 s37, v254, 1
	v_readlane_b32 s38, v254, 2
	v_readlane_b32 s39, v254, 3
	v_readlane_b32 s40, v254, 4
	v_readlane_b32 s41, v254, 5
	v_readlane_b32 s42, v254, 6
	v_readlane_b32 s43, v254, 7
	v_readlane_b32 s44, v254, 8
	v_readlane_b32 s45, v254, 9
	v_readlane_b32 s46, v254, 10
	v_readlane_b32 s47, v254, 11
	v_readlane_b32 s48, v254, 12
	v_readlane_b32 s49, v254, 13
	v_readlane_b32 s50, v254, 14
	v_readlane_b32 s51, v254, 15
	s_mov_b64 s[12:13], s[48:49]
	s_mov_b64 s[14:15], s[50:51]
	s_mov_b64 s[2:3], 0x5000
	s_add_i32 s18, s18, s95
	s_branch .LBB0_1177
